# write-through (sc1) 16B stores for G1, QKV and XC phase outputs: cheaper L2 writeback at the grid-barrier release
# speedup vs baseline: 1.0083x; 1.0083x over previous
.LBB0_217:
	v_lshlrev_b64 v[2:3], 11, v[160:161]
	v_lshl_add_u64 v[2:3], s[6:7], 0, v[2:3]
	v_lshlrev_b32_e32 v138, 1, v145
	v_lshl_add_u64 v[2:3], v[2:3], 0, v[138:139]
	global_store_dwordx4 v[2:3], v[126:129], off sc1
	global_store_dwordx4 v[2:3], v[106:109], off offset:256 sc1
	v_lshlrev_b64 v[2:3], 11, v[158:159]
	v_lshl_add_u64 v[2:3], s[6:7], 0, v[2:3]
	v_lshl_add_u64 v[2:3], v[2:3], 0, v[138:139]
	global_store_dwordx4 v[2:3], v[98:101], off sc1
	global_store_dwordx4 v[2:3], v[90:93], off offset:256 sc1
	v_lshlrev_b64 v[2:3], 11, v[156:157]
	v_lshl_add_u64 v[2:3], s[6:7], 0, v[2:3]
	v_lshl_add_u64 v[2:3], v[2:3], 0, v[138:139]
	global_store_dwordx4 v[2:3], v[82:85], off sc1
	global_store_dwordx4 v[2:3], v[78:81], off offset:256 sc1
	v_lshlrev_b64 v[2:3], 11, v[154:155]
	v_lshl_add_u64 v[2:3], s[6:7], 0, v[2:3]
	v_lshl_add_u64 v[2:3], v[2:3], 0, v[138:139]
	global_store_dwordx4 v[2:3], v[74:77], off sc1
	global_store_dwordx4 v[2:3], v[70:73], off offset:256 sc1
	v_lshlrev_b64 v[2:3], 11, v[152:153]
	v_lshl_add_u64 v[2:3], s[6:7], 0, v[2:3]
	v_lshl_add_u64 v[2:3], v[2:3], 0, v[138:139]
	global_store_dwordx4 v[2:3], v[62:65], off sc1
	global_store_dwordx4 v[2:3], v[42:45], off offset:256 sc1
	v_lshlrev_b64 v[2:3], 11, v[150:151]
	v_lshl_add_u64 v[2:3], s[6:7], 0, v[2:3]
	v_lshl_add_u64 v[2:3], v[2:3], 0, v[138:139]
	global_store_dwordx4 v[2:3], v[34:37], off sc1
	global_store_dwordx4 v[2:3], v[26:29], off offset:256 sc1
	v_lshlrev_b64 v[2:3], 11, v[148:149]
	v_lshl_add_u64 v[2:3], s[6:7], 0, v[2:3]
	v_lshl_add_u64 v[2:3], v[2:3], 0, v[138:139]
	global_store_dwordx4 v[2:3], v[18:21], off sc1
	global_store_dwordx4 v[2:3], v[14:17], off offset:256 sc1
	v_lshlrev_b64 v[2:3], 11, v[146:147]
	v_lshl_add_u64 v[2:3], s[6:7], 0, v[2:3]
	v_lshl_add_u64 v[2:3], v[2:3], 0, v[138:139]
	global_store_dwordx4 v[2:3], v[10:13], off sc1
	global_store_dwordx4 v[2:3], v[6:9], off offset:256 sc1
	s_cbranch_execnz .LBB0_216
.LBB0_218:
	v_lshlrev_b32_e32 v0, 15, v145
	v_and_b32_e32 v138, 0x1b80000, v0
	v_lshlrev_b64 v[2:3], 5, v[160:161]
	v_lshl_add_u64 v[4:5], s[4:5], 0, v[138:139]
	v_lshl_add_u64 v[22:23], v[4:5], 0, v[2:3]
	v_mov_b32_e32 v145, v139
	v_lshl_add_u64 v[22:23], v[22:23], 0, v[144:145]
	global_store_dwordx4 v[22:23], v[126:129], off sc1
	v_lshl_add_u64 v[22:23], v[4:5], 0, s[12:13]
	v_lshl_add_u64 v[2:3], v[22:23], 0, v[2:3]
	v_lshl_add_u64 v[2:3], v[2:3], 0, v[144:145]
	global_store_dwordx4 v[2:3], v[106:109], off sc1
	v_lshlrev_b64 v[2:3], 5, v[158:159]
	v_lshl_add_u64 v[24:25], v[4:5], 0, v[2:3]
	v_lshl_add_u64 v[2:3], v[22:23], 0, v[2:3]
	v_lshl_add_u64 v[2:3], v[2:3], 0, v[144:145]
	v_lshl_add_u64 v[24:25], v[24:25], 0, v[144:145]
	global_store_dwordx4 v[2:3], v[90:93], off sc1
	v_lshlrev_b64 v[2:3], 5, v[156:157]
	global_store_dwordx4 v[24:25], v[98:101], off sc1
	v_lshl_add_u64 v[24:25], v[4:5], 0, v[2:3]
	v_lshl_add_u64 v[2:3], v[22:23], 0, v[2:3]
	v_lshl_add_u64 v[2:3], v[2:3], 0, v[144:145]
	v_lshl_add_u64 v[24:25], v[24:25], 0, v[144:145]
	global_store_dwordx4 v[2:3], v[78:81], off sc1
	v_lshlrev_b64 v[2:3], 5, v[154:155]
	global_store_dwordx4 v[24:25], v[82:85], off sc1
	v_lshl_add_u64 v[24:25], v[4:5], 0, v[2:3]
	v_lshl_add_u64 v[2:3], v[22:23], 0, v[2:3]
	v_lshl_add_u64 v[2:3], v[2:3], 0, v[144:145]
	v_lshl_add_u64 v[24:25], v[24:25], 0, v[144:145]
	global_store_dwordx4 v[2:3], v[70:73], off sc1
	v_lshlrev_b64 v[2:3], 5, v[152:153]
	global_store_dwordx4 v[24:25], v[74:77], off sc1
	v_lshl_add_u64 v[24:25], v[4:5], 0, v[2:3]
	v_lshl_add_u64 v[2:3], v[22:23], 0, v[2:3]
	v_lshl_add_u64 v[2:3], v[2:3], 0, v[144:145]
	v_lshl_add_u64 v[24:25], v[24:25], 0, v[144:145]
	global_store_dwordx4 v[2:3], v[42:45], off sc1
	v_lshlrev_b64 v[2:3], 5, v[150:151]
	global_store_dwordx4 v[24:25], v[62:65], off sc1
	v_lshl_add_u64 v[24:25], v[4:5], 0, v[2:3]
	v_lshl_add_u64 v[2:3], v[22:23], 0, v[2:3]
	v_lshl_add_u64 v[2:3], v[2:3], 0, v[144:145]
	v_lshl_add_u64 v[24:25], v[24:25], 0, v[144:145]
	global_store_dwordx4 v[2:3], v[26:29], off sc1
	v_lshlrev_b64 v[2:3], 5, v[148:149]
	global_store_dwordx4 v[24:25], v[34:37], off sc1
	v_lshl_add_u64 v[24:25], v[4:5], 0, v[2:3]
	v_lshl_add_u64 v[2:3], v[22:23], 0, v[2:3]
	v_lshl_add_u64 v[2:3], v[2:3], 0, v[144:145]
	global_store_dwordx4 v[2:3], v[14:17], off sc1
	v_lshlrev_b64 v[2:3], 5, v[146:147]
	v_lshl_add_u64 v[4:5], v[4:5], 0, v[2:3]
	v_lshl_add_u64 v[2:3], v[22:23], 0, v[2:3]
	v_lshl_add_u64 v[24:25], v[24:25], 0, v[144:145]
	v_lshl_add_u64 v[4:5], v[4:5], 0, v[144:145]
	v_lshl_add_u64 v[2:3], v[2:3], 0, v[144:145]
	global_store_dwordx4 v[24:25], v[18:21], off sc1
	global_store_dwordx4 v[4:5], v[10:13], off sc1
	global_store_dwordx4 v[2:3], v[6:9], off sc1
	s_andn2_b64 vcc, exec, s[20:21]
	s_mov_b64 s[20:21], -1
	s_cbranch_vccnz .LBB0_207

; DEV float siluf_(float x) { return x * __builtin_amdgcn_rcpf(1.f + __expf(-x)); }
; #define LAS __attribute__((address_space(3)))
; DEV uint4 pack8(const float* f) { return make_uint4(pk2(f[0], f[1]), pk2(f[2], f[3]), pk2(f[4], f[5]), pk2(f[6], f[7])); }
; DEV void xc_gates_phase(LAS char* shm, const bf16_t* mi, bf16_t* xc, const bf16_t* WfT, const float* cw, const float* cb, float* gpart  ) {
;     ...
;         auto compute = [&](int c0) {
; #pragma nounroll
;             for (int ks = 0; ks < 4; ++ks) {
;                 const int cl = 32 * ks + 8 * fq, c = c0 + cl;
;                 float xv[8], t8[8];
;                 { const f32x4 b0 = *(const LAS f32x4*)(shm + CWL + 16384 + c * 4), b1 = *(const LAS f32x4*)(shm + CWL + 16384 + c * 4 + 16);
;                   xv[0] = b0[0]; xv[1] = b0[1]; xv[2] = b0[2]; xv[3] = b0[3]; xv[4] = b1[0]; xv[5] = b1[1]; xv[6] = b1[2]; xv[7] = b1[3]; }
;                 u32x4 raw3;
; #pragma unroll
;                 for (int tap = 0; tap < 4; ++tap) {
;                     const u32x4 rw = *(const LAS u32x4*)(stg + (fr + tap) * SRS_ + cl * 2);
;                     if (tap == 3) raw3 = rw;
;                     unpack8(make_uint4(rw[0], rw[1], rw[2], rw[3]), t8);
;                     const f32x4 w0 = *(const LAS f32x4*)(shm + CWL + tap * 4096 + c * 4), w1 = *(const LAS f32x4*)(shm + CWL + tap * 4096 + c * 4 + 16);
;                     xv[0] += t8[0] * w0[0]; xv[1] += t8[1] * w0[1]; xv[2] += t8[2] * w0[2]; xv[3] += t8[3] * w0[3];
;                     xv[4] += t8[4] * w1[0]; xv[5] += t8[5] * w1[1]; xv[6] += t8[6] * w1[2]; xv[7] += t8[7] * w1[3];
;                 }
; #pragma unroll
;                 for (int e = 0; e < 8; ++e) xv[e] = siluf_(xv[e]);
;                 const uint4 xp = pack8(xv);
;                 *(uint4*)(xc + (size_t)(m0 + fr) * DM + c) = xp;
;                 const u32x4 xpu = (u32x4){xp.x, xp.y, xp.z, xp.w};
;                 const bf16x8 bx = *(const LAS bf16x8*)(shm + (fr & 7) * WRS + c * 2);
;                 const bf16x8 bv = *(const LAS bf16x8*)(shm + WIMG + (fr & 7) * WRS + c * 2);
;                 acc = __builtin_amdgcn_mfma_f32_16x16x32_bf16(*(const bf16x8*)&xpu, bx, acc, 0, 0, 0);
;                 acc = __builtin_amdgcn_mfma_f32_16x16x32_bf16(*(const bf16x8*)&raw3, bv, acc, 0, 0, 0);
;             }
.LBB0_358:
	ds_read_b128 v[90:93], v5 offset:16384
	ds_read_b128 v[94:97], v5 offset:16400
	ds_read_b128 v[98:101], v5
	ds_read_b128 v[102:105], v5 offset:16
	ds_read_b128 v[106:109], v89
	ds_read_b128 v[110:113], v89 offset:528
	ds_read_b128 v[114:117], v5 offset:4096
	ds_read_b128 v[118:121], v5 offset:4112
	ds_read_b128 v[122:125], v5 offset:8192
	ds_read_b128 v[126:129], v5 offset:8208
	ds_read_b128 v[130:133], v89 offset:1056
	ds_read_b128 v[50:53], v89 offset:1584
	ds_read_b128 v[134:137], v5 offset:12288
	ds_read_b128 v[138:141], v5 offset:12304
	s_waitcnt lgkmcnt(9)
	v_lshlrev_b32_e32 v152, 16, v106
	v_and_b32_e32 v153, 0xffff0000, v106
	v_lshlrev_b32_e32 v106, 16, v107
	v_and_b32_e32 v107, 0xffff0000, v107
	v_lshlrev_b32_e32 v162, 16, v108
	v_and_b32_e32 v163, 0xffff0000, v108
	v_lshlrev_b32_e32 v108, 16, v109
	v_and_b32_e32 v109, 0xffff0000, v109
	s_waitcnt lgkmcnt(8)
	v_lshlrev_b32_e32 v154, 16, v110
	v_and_b32_e32 v155, 0xffff0000, v110
	v_lshlrev_b32_e32 v110, 16, v111
	v_and_b32_e32 v111, 0xffff0000, v111
	v_lshlrev_b32_e32 v164, 16, v112
	v_and_b32_e32 v165, 0xffff0000, v112
	v_lshlrev_b32_e32 v112, 16, v113
	v_and_b32_e32 v113, 0xffff0000, v113
	v_pk_fma_f32 v[90:91], v[98:99], v[152:153], v[90:91]
	v_pk_fma_f32 v[92:93], v[100:101], v[106:107], v[92:93]
	v_pk_fma_f32 v[94:95], v[102:103], v[162:163], v[94:95]
	v_pk_fma_f32 v[96:97], v[104:105], v[108:109], v[96:97]
	s_waitcnt lgkmcnt(3)
	v_lshlrev_b32_e32 v156, 16, v130
	v_and_b32_e32 v157, 0xffff0000, v130
	v_lshlrev_b32_e32 v130, 16, v131
	v_and_b32_e32 v131, 0xffff0000, v131
	v_lshlrev_b32_e32 v166, 16, v132
	v_and_b32_e32 v167, 0xffff0000, v132
	v_lshlrev_b32_e32 v132, 16, v133
	v_and_b32_e32 v133, 0xffff0000, v133
	v_pk_fma_f32 v[90:91], v[114:115], v[154:155], v[90:91]
	v_pk_fma_f32 v[92:93], v[116:117], v[110:111], v[92:93]
	v_pk_fma_f32 v[94:95], v[118:119], v[164:165], v[94:95]
	v_pk_fma_f32 v[96:97], v[120:121], v[112:113], v[96:97]
	s_waitcnt lgkmcnt(2)
	v_lshlrev_b32_e32 v158, 16, v50
	v_and_b32_e32 v159, 0xffff0000, v50
	v_lshlrev_b32_e32 v160, 16, v51
	v_and_b32_e32 v161, 0xffff0000, v51
	v_lshlrev_b32_e32 v168, 16, v52
	v_and_b32_e32 v169, 0xffff0000, v52
	v_lshlrev_b32_e32 v170, 16, v53
	v_and_b32_e32 v171, 0xffff0000, v53
	v_pk_fma_f32 v[90:91], v[122:123], v[156:157], v[90:91]
	v_pk_fma_f32 v[92:93], v[124:125], v[130:131], v[92:93]
	v_pk_fma_f32 v[94:95], v[126:127], v[166:167], v[94:95]
	v_pk_fma_f32 v[96:97], v[128:129], v[132:133], v[96:97]
	s_waitcnt lgkmcnt(1)
	v_pk_fma_f32 v[90:91], v[134:135], v[158:159], v[90:91]
	v_pk_fma_f32 v[92:93], v[136:137], v[160:161], v[92:93]
	s_waitcnt lgkmcnt(0)
	v_pk_fma_f32 v[94:95], v[138:139], v[168:169], v[94:95]
	v_pk_fma_f32 v[96:97], v[140:141], v[170:171], v[96:97]
	v_mul_f32_e32 v0, 0xbfb8aa3b, v90
	v_mul_f32_e32 v1, 0xbfb8aa3b, v91
	v_mul_f32_e32 v98, 0xbfb8aa3b, v92
	v_mul_f32_e32 v99, 0xbfb8aa3b, v93
	v_mul_f32_e32 v100, 0xbfb8aa3b, v94
	v_mul_f32_e32 v101, 0xbfb8aa3b, v95
	v_mul_f32_e32 v102, 0xbfb8aa3b, v96
	v_mul_f32_e32 v103, 0xbfb8aa3b, v97
	v_exp_f32_e32 v0, v0
	v_exp_f32_e32 v1, v1
	v_exp_f32_e32 v98, v98
	v_exp_f32_e32 v99, v99
	v_exp_f32_e32 v100, v100
	v_exp_f32_e32 v101, v101
	v_exp_f32_e32 v102, v102
	v_exp_f32_e32 v103, v103
	v_add_f32_e32 v0, 1.0, v0
	v_add_f32_e32 v1, 1.0, v1
	v_add_f32_e32 v104, 1.0, v98
	v_add_f32_e32 v105, 1.0, v99
	v_add_f32_e32 v106, 1.0, v100
	v_add_f32_e32 v107, 1.0, v101
	v_add_f32_e32 v108, 1.0, v102
	v_add_f32_e32 v109, 1.0, v103
	v_rcp_f32_e32 v98, v0
	v_rcp_f32_e32 v99, v1
	v_rcp_f32_e32 v100, v104
	v_rcp_f32_e32 v101, v105
	v_rcp_f32_e32 v102, v106
	v_rcp_f32_e32 v103, v107
	v_rcp_f32_e32 v104, v108
	v_rcp_f32_e32 v105, v109
	v_pk_mul_f32 v[90:91], v[90:91], v[98:99]
	v_pk_mul_f32 v[92:93], v[92:93], v[100:101]
	v_pk_mul_f32 v[94:95], v[94:95], v[102:103]
	v_pk_mul_f32 v[96:97], v[96:97], v[104:105]
	v_cvt_pk_bf16_f32 v90, v90, v91
	v_cvt_pk_bf16_f32 v91, v92, v93
	v_cvt_pk_bf16_f32 v92, v94, v95
	v_cvt_pk_bf16_f32 v93, v96, v97
	ds_read_b128 v[142:145], v3
	ds_read_b128 v[146:149], v3 offset:16512
	s_waitcnt lgkmcnt(1)
	v_mfma_f32_16x16x32_bf16 v[38:41], v[90:93], v[142:145], v[38:41]
	v_lshl_add_u64 v[150:151], v[74:75], 0, s[26:27]
	s_add_u32 s26, s26, 64
	v_add_co_u32_e32 v94, vcc, s31, v150
	s_waitcnt lgkmcnt(0)
	v_mfma_f32_16x16x32_bf16 v[38:41], v[50:53], v[146:149], v[38:41]
	s_addc_u32 s27, s27, 0
	v_add_u32_e32 v89, 64, v89
	v_add_u32_e32 v3, 64, v3
	v_add_u32_e32 v5, 0x80, v5
	v_addc_co_u32_e32 v95, vcc, 0, v151, vcc
	s_cmpk_eq_i32 s26, 0x100
	global_store_dwordx4 v[94:95], v[90:93], off sc1
	s_cbranch_scc0 .LBB0_358
	ds_write_b128 v87, v[18:21] offset:53504
	ds_write_b128 v87, v[26:29] offset:55616
	ds_write_b128 v87, v[34:37] offset:57728
	ds_write_b128 v87, v[42:45] offset:59840
	s_and_saveexec_b64 s[0:1], s[4:5]
	ds_write_b128 v88, v[46:49] offset:53504
	s_or_b64 exec, exec, s[0:1]
	s_and_b64 vcc, exec, s[24:25]
	s_cbranch_vccz .LBB0_373
	v_mov_b32_e32 v28, v2
	v_mov_b32_e32 v29, v2
	v_mov_b64_e32 v[20:21], v[28:29]
	v_mov_b64_e32 v[18:19], v[28:29]
	s_and_saveexec_b64 s[0:1], s[6:7]
	s_cbranch_execz .LBB0_364
	global_load_dwordx4 v[18:21], v[64:65], off offset:768

; DEV void xc_gates_phase(LAS char* shm, const bf16_t* mi, bf16_t* xc, const bf16_t* WfT, const float* cw, const float* cb, float* gpart  ) {
;     ...
;             for (int ks = 0; ks < 4; ++ks) {
;                 const int cl = 32 * ks + 8 * fq, c = c0 + cl;
;                 float xv[8], t8[8];
;                 { const f32x4 b0 = *(const LAS f32x4*)(shm + CWL + 16384 + c * 4), b1 = *(const LAS f32x4*)(shm + CWL + 16384 + c * 4 + 16);
;                   xv[0] = b0[0]; xv[1] = b0[1]; xv[2] = b0[2]; xv[3] = b0[3]; xv[4] = b1[0]; xv[5] = b1[1]; xv[6] = b1[2]; xv[7] = b1[3]; }
;                 u32x4 raw3;
; #pragma unroll
;                 for (int tap = 0; tap < 4; ++tap) {
;                     const u32x4 rw = *(const LAS u32x4*)(stg + (fr + tap) * SRS_ + cl * 2);
;                     if (tap == 3) raw3 = rw;
;                     unpack8(make_uint4(rw[0], rw[1], rw[2], rw[3]), t8);
;                     const f32x4 w0 = *(const LAS f32x4*)(shm + CWL + tap * 4096 + c * 4), w1 = *(const LAS f32x4*)(shm + CWL + tap * 4096 + c * 4 + 16);
;                     xv[0] += t8[0] * w0[0]; xv[1] += t8[1] * w0[1]; xv[2] += t8[2] * w0[2]; xv[3] += t8[3] * w0[3];
;                     xv[4] += t8[4] * w1[0]; xv[5] += t8[5] * w1[1]; xv[6] += t8[6] * w1[2]; xv[7] += t8[7] * w1[3];
;                 }
; #pragma unroll
;                 for (int e = 0; e < 8; ++e) xv[e] = siluf_(xv[e]);
;                 const uint4 xp = pack8(xv);
;                 *(uint4*)(xc + (size_t)(m0 + fr) * DM + c) = xp;
;                 const u32x4 xpu = (u32x4){xp.x, xp.y, xp.z, xp.w};
;                 const bf16x8 bx = *(const LAS bf16x8*)(shm + (fr & 7) * WRS + c * 2);
;                 const bf16x8 bv = *(const LAS bf16x8*)(shm + WIMG + (fr & 7) * WRS + c * 2);
;                 acc = __builtin_amdgcn_mfma_f32_16x16x32_bf16(*(const bf16x8*)&xpu, bx, acc, 0, 0, 0);
;                 acc = __builtin_amdgcn_mfma_f32_16x16x32_bf16(*(const bf16x8*)&raw3, bv, acc, 0, 0, 0);
;             }
;         };
;         XC_LOAD(pr0, 0); XC_LOAD(pr1, 1);
; #pragma nounroll
;         for (int sp = 0; sp < 2; ++sp) {
;             XC_STAGE(pr0); if (sp == 0) XC_LOAD(pr0, 2);
;             compute(chalf * 512 + (2 * sp) * 128);
;             XC_STAGE(pr1); if (sp == 0) XC_LOAD(pr1, 3);
;             compute(chalf * 512 + (2 * sp + 1) * 128);
;         }
;     ...
;         if (fr < 8) {
; #pragma unroll
.LBB0_374:
	ds_read_b128 v[90:93], v74 offset:16384
	ds_read_b128 v[94:97], v74 offset:16400
	ds_read_b128 v[98:101], v74
	ds_read_b128 v[102:105], v74 offset:16
	ds_read_b128 v[106:109], v75
	ds_read_b128 v[110:113], v75 offset:528
	ds_read_b128 v[114:117], v74 offset:4096
	ds_read_b128 v[118:121], v74 offset:4112
	ds_read_b128 v[122:125], v74 offset:8192
	ds_read_b128 v[126:129], v74 offset:8208
	ds_read_b128 v[130:133], v75 offset:1056
	ds_read_b128 v[50:53], v75 offset:1584
	ds_read_b128 v[134:137], v74 offset:12288
	ds_read_b128 v[138:141], v74 offset:12304
	s_waitcnt lgkmcnt(9)
	v_lshlrev_b32_e32 v152, 16, v106
	v_and_b32_e32 v153, 0xffff0000, v106
	v_lshlrev_b32_e32 v106, 16, v107
	v_and_b32_e32 v107, 0xffff0000, v107
	v_lshlrev_b32_e32 v162, 16, v108
	v_and_b32_e32 v163, 0xffff0000, v108
	v_lshlrev_b32_e32 v108, 16, v109
	v_and_b32_e32 v109, 0xffff0000, v109
	s_waitcnt lgkmcnt(8)
	v_lshlrev_b32_e32 v154, 16, v110
	v_and_b32_e32 v155, 0xffff0000, v110
	v_lshlrev_b32_e32 v110, 16, v111
	v_and_b32_e32 v111, 0xffff0000, v111
	v_lshlrev_b32_e32 v164, 16, v112
	v_and_b32_e32 v165, 0xffff0000, v112
	v_lshlrev_b32_e32 v112, 16, v113
	v_and_b32_e32 v113, 0xffff0000, v113
	v_pk_fma_f32 v[90:91], v[98:99], v[152:153], v[90:91]
	v_pk_fma_f32 v[92:93], v[100:101], v[106:107], v[92:93]
	v_pk_fma_f32 v[94:95], v[102:103], v[162:163], v[94:95]
	v_pk_fma_f32 v[96:97], v[104:105], v[108:109], v[96:97]
	s_waitcnt lgkmcnt(3)
	v_lshlrev_b32_e32 v156, 16, v130
	v_and_b32_e32 v157, 0xffff0000, v130
	v_lshlrev_b32_e32 v130, 16, v131
	v_and_b32_e32 v131, 0xffff0000, v131
	v_lshlrev_b32_e32 v166, 16, v132
	v_and_b32_e32 v167, 0xffff0000, v132
	v_lshlrev_b32_e32 v132, 16, v133
	v_and_b32_e32 v133, 0xffff0000, v133
	v_pk_fma_f32 v[90:91], v[114:115], v[154:155], v[90:91]
	v_pk_fma_f32 v[92:93], v[116:117], v[110:111], v[92:93]
	v_pk_fma_f32 v[94:95], v[118:119], v[164:165], v[94:95]
	v_pk_fma_f32 v[96:97], v[120:121], v[112:113], v[96:97]
	s_waitcnt lgkmcnt(2)
	v_lshlrev_b32_e32 v158, 16, v50
	v_and_b32_e32 v159, 0xffff0000, v50
	v_lshlrev_b32_e32 v160, 16, v51
	v_and_b32_e32 v161, 0xffff0000, v51
	v_lshlrev_b32_e32 v168, 16, v52
	v_and_b32_e32 v169, 0xffff0000, v52
	v_lshlrev_b32_e32 v170, 16, v53
	v_and_b32_e32 v171, 0xffff0000, v53
	v_pk_fma_f32 v[90:91], v[122:123], v[156:157], v[90:91]
	v_pk_fma_f32 v[92:93], v[124:125], v[130:131], v[92:93]
	v_pk_fma_f32 v[94:95], v[126:127], v[166:167], v[94:95]
	v_pk_fma_f32 v[96:97], v[128:129], v[132:133], v[96:97]
	s_waitcnt lgkmcnt(1)
	v_pk_fma_f32 v[90:91], v[134:135], v[158:159], v[90:91]
	v_pk_fma_f32 v[92:93], v[136:137], v[160:161], v[92:93]
	s_waitcnt lgkmcnt(0)
	v_pk_fma_f32 v[94:95], v[138:139], v[168:169], v[94:95]
	v_pk_fma_f32 v[96:97], v[140:141], v[170:171], v[96:97]
	v_mul_f32_e32 v0, 0xbfb8aa3b, v90
	v_mul_f32_e32 v1, 0xbfb8aa3b, v91
	v_mul_f32_e32 v89, 0xbfb8aa3b, v92
	v_mul_f32_e32 v98, 0xbfb8aa3b, v93
	v_mul_f32_e32 v99, 0xbfb8aa3b, v94
	v_mul_f32_e32 v100, 0xbfb8aa3b, v95
	v_mul_f32_e32 v101, 0xbfb8aa3b, v96
	v_mul_f32_e32 v102, 0xbfb8aa3b, v97
	v_exp_f32_e32 v0, v0
	v_exp_f32_e32 v1, v1
	v_exp_f32_e32 v89, v89
	v_exp_f32_e32 v98, v98
	v_exp_f32_e32 v99, v99
	v_exp_f32_e32 v100, v100
	v_exp_f32_e32 v101, v101
	v_exp_f32_e32 v102, v102
	v_add_f32_e32 v0, 1.0, v0
	v_add_f32_e32 v1, 1.0, v1
	v_add_f32_e32 v89, 1.0, v89
	v_add_f32_e32 v103, 1.0, v98
	v_add_f32_e32 v104, 1.0, v99
	v_add_f32_e32 v105, 1.0, v100
	v_add_f32_e32 v106, 1.0, v101
	v_add_f32_e32 v107, 1.0, v102
	v_rcp_f32_e32 v98, v0
	v_rcp_f32_e32 v99, v1
	v_rcp_f32_e32 v100, v89
	v_rcp_f32_e32 v101, v103
	v_rcp_f32_e32 v102, v104
	v_rcp_f32_e32 v103, v105
	v_rcp_f32_e32 v104, v106
	v_rcp_f32_e32 v105, v107
	v_pk_mul_f32 v[90:91], v[90:91], v[98:99]
	v_pk_mul_f32 v[92:93], v[92:93], v[100:101]
	v_pk_mul_f32 v[94:95], v[94:95], v[102:103]
	v_pk_mul_f32 v[96:97], v[96:97], v[104:105]
	v_cvt_pk_bf16_f32 v90, v90, v91
	v_cvt_pk_bf16_f32 v91, v92, v93
	v_cvt_pk_bf16_f32 v92, v94, v95
	v_cvt_pk_bf16_f32 v93, v96, v97
	ds_read_b128 v[142:145], v3
	ds_read_b128 v[146:149], v3 offset:16512
	s_waitcnt lgkmcnt(1)
	v_mfma_f32_16x16x32_bf16 v[38:41], v[90:93], v[142:145], v[38:41]
	v_lshl_add_u64 v[150:151], v[4:5], 0, s[24:25]
	s_add_u32 s24, s24, 64
	v_add_co_u32_e32 v94, vcc, s31, v150
	s_waitcnt lgkmcnt(0)
	v_mfma_f32_16x16x32_bf16 v[38:41], v[50:53], v[146:149], v[38:41]
	s_addc_u32 s25, s25, 0
	v_add_u32_e32 v75, 64, v75
	v_add_u32_e32 v3, 64, v3
	v_add_u32_e32 v74, 0x80, v74
	v_addc_co_u32_e32 v95, vcc, 0, v151, vcc
	s_cmpk_lg_i32 s24, 0x100
	global_store_dwordx4 v[94:95], v[90:93], off offset:256 sc1
	s_cbranch_scc1 .LBB0_374
	s_movk_i32 s19, 0x100
	s_mov_b64 s[24:25], 0
	s_and_b64 vcc, exec, s[22:23]
	s_cbranch_vccz .LBB0_343
	s_and_saveexec_b64 s[0:1], s[14:15]
	s_cbranch_execz .LBB0_321
	s_ashr_i32 s19, s18, 31
	v_lshl_add_u64 v[4:5], s[18:19], 0, v[58:59]
	v_lshlrev_b64 v[4:5], 5, v[4:5]
	v_lshl_add_u64 v[4:5], v[54:55], 0, v[4:5]
	global_store_dword v[4:5], v38, off
	global_store_dword v[4:5], v39, off offset:32
	global_store_dword v[4:5], v40, off offset:64
	global_store_dword v[4:5], v41, off offset:96
	s_branch .LBB0_321

.LBB0_527:
	s_cmp_lt_u32 s73, 8
	s_cselect_b64 vcc, -1, 0
	s_and_b64 s[0:1], vcc, exec
	s_cselect_b32 s1, s66, s68
	s_cselect_b32 s0, s65, s67
	s_lshl_b32 s15, s73, 8
	s_and_b32 s15, s15, 0x300
	v_or_b32_e32 v0, s15, v150
	v_lshl_add_u32 v146, s13, 8, v148
	v_cndmask_b32_e32 v142, 1.0, v154, vcc
	v_lshlrev_b32_e32 v138, 1, v0
	v_ashrrev_i32_e32 v147, 31, v146
	v_lshl_add_u64 v[144:145], s[0:1], 0, v[138:139]
	v_lshlrev_b64 v[0:1], 11, v[146:147]
	v_pk_mul_f32 v[158:159], v[142:143], v[128:129] op_sel_hi:[0,1]
	v_pk_mul_f32 v[156:157], v[142:143], v[126:127] op_sel_hi:[0,1]
	v_pk_mul_f32 v[160:161], v[142:143], v[124:125] op_sel_hi:[0,1]
	v_pk_mul_f32 v[162:163], v[142:143], v[122:123] op_sel_hi:[0,1]
	v_lshl_add_u64 v[0:1], v[144:145], 0, v[0:1]
	v_cvt_pk_bf16_f32 v156, v156, v157
	v_cvt_pk_bf16_f32 v157, v158, v159
	v_cvt_pk_bf16_f32 v158, v162, v163
	v_cvt_pk_bf16_f32 v159, v160, v161
	global_store_dwordx4 v[0:1], v[156:159], off sc1
	v_pk_mul_f32 v[160:161], v[142:143], v[108:109] op_sel_hi:[0,1]
	v_pk_mul_f32 v[162:163], v[142:143], v[106:107] op_sel_hi:[0,1]
	v_pk_mul_f32 v[158:159], v[142:143], v[112:113] op_sel_hi:[0,1]
	v_pk_mul_f32 v[156:157], v[142:143], v[110:111] op_sel_hi:[0,1]
	v_cvt_pk_bf16_f32 v156, v156, v157
	v_cvt_pk_bf16_f32 v157, v158, v159
	v_cvt_pk_bf16_f32 v158, v162, v163
	v_cvt_pk_bf16_f32 v159, v160, v161
	global_store_dwordx4 v[0:1], v[156:159], off offset:256 sc1
	v_or_b32_e32 v0, 16, v146
	v_ashrrev_i32_e32 v1, 31, v0
	v_lshlrev_b64 v[0:1], 11, v[0:1]
	v_pk_mul_f32 v[158:159], v[142:143], v[120:121] op_sel_hi:[0,1]
	v_pk_mul_f32 v[156:157], v[142:143], v[118:119] op_sel_hi:[0,1]
	v_pk_mul_f32 v[160:161], v[142:143], v[116:117] op_sel_hi:[0,1]
	v_pk_mul_f32 v[162:163], v[142:143], v[114:115] op_sel_hi:[0,1]
	v_lshl_add_u64 v[0:1], v[144:145], 0, v[0:1]
	v_cvt_pk_bf16_f32 v156, v156, v157
	v_cvt_pk_bf16_f32 v157, v158, v159
	v_cvt_pk_bf16_f32 v158, v162, v163
	v_cvt_pk_bf16_f32 v159, v160, v161
	global_store_dwordx4 v[0:1], v[156:159], off sc1
	v_pk_mul_f32 v[160:161], v[142:143], v[92:93] op_sel_hi:[0,1]
	v_pk_mul_f32 v[162:163], v[142:143], v[90:91] op_sel_hi:[0,1]
	v_pk_mul_f32 v[158:159], v[142:143], v[96:97] op_sel_hi:[0,1]
	v_pk_mul_f32 v[156:157], v[142:143], v[94:95] op_sel_hi:[0,1]
	v_cvt_pk_bf16_f32 v156, v156, v157
	v_cvt_pk_bf16_f32 v157, v158, v159
	v_cvt_pk_bf16_f32 v158, v162, v163
	v_cvt_pk_bf16_f32 v159, v160, v161
	global_store_dwordx4 v[0:1], v[156:159], off offset:256 sc1
	v_or_b32_e32 v0, 32, v146
	v_ashrrev_i32_e32 v1, 31, v0
	v_lshlrev_b64 v[0:1], 11, v[0:1]
	v_pk_mul_f32 v[158:159], v[142:143], v[104:105] op_sel_hi:[0,1]
	v_pk_mul_f32 v[156:157], v[142:143], v[102:103] op_sel_hi:[0,1]
	v_pk_mul_f32 v[160:161], v[142:143], v[100:101] op_sel_hi:[0,1]
	v_pk_mul_f32 v[162:163], v[142:143], v[98:99] op_sel_hi:[0,1]
	v_lshl_add_u64 v[0:1], v[144:145], 0, v[0:1]
	v_cvt_pk_bf16_f32 v156, v156, v157
	v_cvt_pk_bf16_f32 v157, v158, v159
	v_cvt_pk_bf16_f32 v158, v162, v163
	v_cvt_pk_bf16_f32 v159, v160, v161
	global_store_dwordx4 v[0:1], v[156:159], off sc1
	v_pk_mul_f32 v[160:161], v[142:143], v[76:77] op_sel_hi:[0,1]
	v_pk_mul_f32 v[162:163], v[142:143], v[74:75] op_sel_hi:[0,1]
	v_pk_mul_f32 v[158:159], v[142:143], v[80:81] op_sel_hi:[0,1]
	v_pk_mul_f32 v[156:157], v[142:143], v[78:79] op_sel_hi:[0,1]
	v_cvt_pk_bf16_f32 v156, v156, v157
	v_cvt_pk_bf16_f32 v157, v158, v159
	v_cvt_pk_bf16_f32 v158, v162, v163
	v_cvt_pk_bf16_f32 v159, v160, v161
	global_store_dwordx4 v[0:1], v[156:159], off offset:256 sc1
	v_or_b32_e32 v0, 48, v146
	v_ashrrev_i32_e32 v1, 31, v0
	v_lshlrev_b64 v[0:1], 11, v[0:1]
	v_pk_mul_f32 v[158:159], v[142:143], v[88:89] op_sel_hi:[0,1]
	v_pk_mul_f32 v[156:157], v[142:143], v[86:87] op_sel_hi:[0,1]
	v_pk_mul_f32 v[160:161], v[142:143], v[84:85] op_sel_hi:[0,1]
	v_pk_mul_f32 v[162:163], v[142:143], v[82:83] op_sel_hi:[0,1]
	v_lshl_add_u64 v[0:1], v[144:145], 0, v[0:1]
	v_cvt_pk_bf16_f32 v156, v156, v157
	v_cvt_pk_bf16_f32 v157, v158, v159
	v_cvt_pk_bf16_f32 v158, v162, v163
	v_cvt_pk_bf16_f32 v159, v160, v161
	global_store_dwordx4 v[0:1], v[156:159], off sc1
	v_pk_mul_f32 v[160:161], v[142:143], v[68:69] op_sel_hi:[0,1]
	v_pk_mul_f32 v[162:163], v[142:143], v[66:67] op_sel_hi:[0,1]
	v_pk_mul_f32 v[158:159], v[142:143], v[72:73] op_sel_hi:[0,1]
	v_pk_mul_f32 v[156:157], v[142:143], v[70:71] op_sel_hi:[0,1]
	v_cvt_pk_bf16_f32 v156, v156, v157
	v_cvt_pk_bf16_f32 v157, v158, v159
	v_cvt_pk_bf16_f32 v158, v162, v163
	v_cvt_pk_bf16_f32 v159, v160, v161
	global_store_dwordx4 v[0:1], v[156:159], off offset:256 sc1
	v_add_u32_e32 v0, 0x80, v146
	v_ashrrev_i32_e32 v1, 31, v0
	v_lshlrev_b64 v[0:1], 11, v[0:1]
	v_pk_mul_f32 v[158:159], v[142:143], v[64:65] op_sel_hi:[0,1]
	v_pk_mul_f32 v[156:157], v[142:143], v[62:63] op_sel_hi:[0,1]
	v_pk_mul_f32 v[160:161], v[142:143], v[60:61] op_sel_hi:[0,1]
	v_pk_mul_f32 v[162:163], v[142:143], v[58:59] op_sel_hi:[0,1]
	v_lshl_add_u64 v[0:1], v[144:145], 0, v[0:1]
	v_cvt_pk_bf16_f32 v156, v156, v157
	v_cvt_pk_bf16_f32 v157, v158, v159
	v_cvt_pk_bf16_f32 v158, v162, v163
	v_cvt_pk_bf16_f32 v159, v160, v161
	global_store_dwordx4 v[0:1], v[156:159], off sc1
	v_pk_mul_f32 v[160:161], v[142:143], v[44:45] op_sel_hi:[0,1]
	v_pk_mul_f32 v[162:163], v[142:143], v[42:43] op_sel_hi:[0,1]
	v_pk_mul_f32 v[158:159], v[142:143], v[52:53] op_sel_hi:[0,1]
	v_pk_mul_f32 v[156:157], v[142:143], v[50:51] op_sel_hi:[0,1]
	v_cvt_pk_bf16_f32 v156, v156, v157
	v_cvt_pk_bf16_f32 v157, v158, v159
	v_cvt_pk_bf16_f32 v158, v162, v163
	v_cvt_pk_bf16_f32 v159, v160, v161
	global_store_dwordx4 v[0:1], v[156:159], off offset:256 sc1
	v_add_u32_e32 v0, 0x90, v146
	v_ashrrev_i32_e32 v1, 31, v0
	v_lshlrev_b64 v[0:1], 11, v[0:1]
	v_pk_mul_f32 v[158:159], v[142:143], v[56:57] op_sel_hi:[0,1]
	v_pk_mul_f32 v[156:157], v[142:143], v[54:55] op_sel_hi:[0,1]
	v_pk_mul_f32 v[160:161], v[142:143], v[48:49] op_sel_hi:[0,1]
	v_pk_mul_f32 v[162:163], v[142:143], v[46:47] op_sel_hi:[0,1]
	v_lshl_add_u64 v[0:1], v[144:145], 0, v[0:1]
	v_cvt_pk_bf16_f32 v156, v156, v157
	v_cvt_pk_bf16_f32 v157, v158, v159
	v_cvt_pk_bf16_f32 v158, v162, v163
	v_cvt_pk_bf16_f32 v159, v160, v161
	global_store_dwordx4 v[0:1], v[156:159], off sc1
	v_pk_mul_f32 v[160:161], v[142:143], v[28:29] op_sel_hi:[0,1]
	v_pk_mul_f32 v[162:163], v[142:143], v[26:27] op_sel_hi:[0,1]
	v_pk_mul_f32 v[158:159], v[142:143], v[36:37] op_sel_hi:[0,1]
	v_pk_mul_f32 v[156:157], v[142:143], v[34:35] op_sel_hi:[0,1]
	v_cvt_pk_bf16_f32 v156, v156, v157
	v_cvt_pk_bf16_f32 v157, v158, v159
	v_cvt_pk_bf16_f32 v158, v162, v163
	v_cvt_pk_bf16_f32 v159, v160, v161
	global_store_dwordx4 v[0:1], v[156:159], off offset:256 sc1
	v_add_u32_e32 v0, 0xa0, v146
	v_ashrrev_i32_e32 v1, 31, v0
	v_lshlrev_b64 v[0:1], 11, v[0:1]
	v_pk_mul_f32 v[158:159], v[142:143], v[40:41] op_sel_hi:[0,1]
	v_pk_mul_f32 v[156:157], v[142:143], v[38:39] op_sel_hi:[0,1]
	v_pk_mul_f32 v[160:161], v[142:143], v[32:33] op_sel_hi:[0,1]
	v_pk_mul_f32 v[162:163], v[142:143], v[30:31] op_sel_hi:[0,1]
	v_lshl_add_u64 v[0:1], v[144:145], 0, v[0:1]
	v_cvt_pk_bf16_f32 v156, v156, v157
	v_cvt_pk_bf16_f32 v157, v158, v159
	v_cvt_pk_bf16_f32 v158, v162, v163
	v_cvt_pk_bf16_f32 v159, v160, v161
	global_store_dwordx4 v[0:1], v[156:159], off sc1
	v_pk_mul_f32 v[160:161], v[142:143], v[12:13] op_sel_hi:[0,1]
	v_pk_mul_f32 v[162:163], v[142:143], v[10:11] op_sel_hi:[0,1]
	v_pk_mul_f32 v[158:159], v[142:143], v[20:21] op_sel_hi:[0,1]
	v_pk_mul_f32 v[156:157], v[142:143], v[18:19] op_sel_hi:[0,1]
	v_cvt_pk_bf16_f32 v156, v156, v157
	v_cvt_pk_bf16_f32 v157, v158, v159
	v_cvt_pk_bf16_f32 v158, v162, v163
	v_cvt_pk_bf16_f32 v159, v160, v161
	global_store_dwordx4 v[0:1], v[156:159], off offset:256 sc1
	v_add_u32_e32 v0, 0xb0, v146
	v_ashrrev_i32_e32 v1, 31, v0
	v_lshlrev_b64 v[0:1], 11, v[0:1]
	v_lshl_add_u64 v[0:1], v[144:145], 0, v[0:1]
	v_pk_mul_f32 v[146:147], v[142:143], v[24:25] op_sel_hi:[0,1]
	v_pk_mul_f32 v[144:145], v[142:143], v[22:23] op_sel_hi:[0,1]
	v_pk_mul_f32 v[156:157], v[142:143], v[16:17] op_sel_hi:[0,1]
	v_pk_mul_f32 v[158:159], v[142:143], v[14:15] op_sel_hi:[0,1]
	v_cvt_pk_bf16_f32 v144, v144, v145
	v_cvt_pk_bf16_f32 v145, v146, v147
	v_cvt_pk_bf16_f32 v146, v158, v159
	v_cvt_pk_bf16_f32 v147, v156, v157
	global_store_dwordx4 v[0:1], v[144:147], off sc1
	v_pk_mul_f32 v[156:157], v[142:143], v[4:5] op_sel_hi:[0,1]
	v_pk_mul_f32 v[158:159], v[142:143], v[2:3] op_sel_hi:[0,1]
	v_pk_mul_f32 v[146:147], v[142:143], v[8:9] op_sel_hi:[0,1]
	v_pk_mul_f32 v[144:145], v[142:143], v[6:7] op_sel_hi:[0,1]
	v_cvt_pk_bf16_f32 v144, v144, v145
	v_cvt_pk_bf16_f32 v145, v146, v147
	v_cvt_pk_bf16_f32 v146, v158, v159
	v_cvt_pk_bf16_f32 v147, v156, v157
	global_store_dwordx4 v[0:1], v[144:147], off offset:256 sc1
	s_cbranch_execnz .LBB0_525
.LBB0_528:
	s_lshl_b32 s0, s13, 8
	s_add_i32 s0, s0, s69
	s_lshr_b32 s1, s0, 9
	s_and_b32 s1, s1, 0x3ffffc
	v_or_b32_e32 v138, s0, v143
	s_or_b32 s1, s1, s73
	s_lshr_b32 s0, s0, 1
	s_lshl_b32 s1, s1, 10
	s_and_b32 s0, s0, 0x3e0
	s_or_b32 s0, s1, s0
	s_ashr_i32 s1, s0, 31
	s_lshl_b64 s[24:25], s[0:1], 10
	v_lshl_add_u64 v[0:1], v[140:141], 0, s[24:25]
	s_or_b32 s24, s0, 8
	s_mov_b32 s13, s9
	s_ashr_i32 s25, s24, 31
	v_cvt_pk_bf16_f32 v126, v126, v127
	v_cvt_pk_bf16_f32 v127, v128, v129
	v_cvt_pk_bf16_f32 v128, v122, v123
	v_lshl_add_u64 v[122:123], v[0:1], 0, s[8:9]
	v_cvt_pk_bf16_f32 v110, v110, v111
	v_cvt_pk_bf16_f32 v111, v112, v113
	v_cvt_pk_bf16_f32 v112, v106, v107
	v_cvt_pk_bf16_f32 v113, v108, v109
	v_lshl_add_u64 v[0:1], v[0:1], 0, s[12:13]
	s_lshl_b64 s[24:25], s[24:25], 10
	global_store_dwordx4 v[0:1], v[110:113], off sc1
	v_lshl_add_u64 v[0:1], v[140:141], 0, s[24:25]
	s_or_b32 s24, s0, 16
	s_ashr_i32 s25, s24, 31
	v_lshl_add_u64 v[110:111], v[0:1], 0, s[8:9]
	v_cvt_pk_bf16_f32 v94, v94, v95
	v_cvt_pk_bf16_f32 v95, v96, v97
	v_cvt_pk_bf16_f32 v96, v90, v91
	v_cvt_pk_bf16_f32 v97, v92, v93
	v_lshl_add_u64 v[0:1], v[0:1], 0, s[12:13]
	s_lshl_b64 s[24:25], s[24:25], 10
	s_or_b32 s0, s0, 24
	global_store_dwordx4 v[0:1], v[94:97], off sc1
	v_lshl_add_u64 v[0:1], v[140:141], 0, s[24:25]
	s_ashr_i32 s1, s0, 31
	v_lshl_add_u64 v[94:95], v[0:1], 0, s[8:9]
	v_cvt_pk_bf16_f32 v78, v78, v79
	v_cvt_pk_bf16_f32 v79, v80, v81
	v_cvt_pk_bf16_f32 v80, v74, v75
	v_cvt_pk_bf16_f32 v81, v76, v77
	v_lshl_add_u64 v[0:1], v[0:1], 0, s[12:13]
	s_lshl_b64 s[0:1], s[0:1], 10
	global_store_dwordx4 v[0:1], v[78:81], off sc1
	v_lshl_add_u64 v[0:1], v[140:141], 0, s[0:1]
	v_cvt_pk_bf16_f32 v70, v70, v71
	v_lshl_add_u64 v[78:79], v[0:1], 0, s[8:9]
	v_cvt_pk_bf16_f32 v71, v72, v73
	v_cvt_pk_bf16_f32 v72, v66, v67
	v_cvt_pk_bf16_f32 v73, v68, v69
	v_lshl_add_u64 v[0:1], v[0:1], 0, s[12:13]
	global_store_dwordx4 v[0:1], v[70:73], off sc1
	v_add_u32_e32 v0, 0x80, v138
	v_lshrrev_b32_e32 v1, 9, v0
	v_and_b32_e32 v1, 0x3ffffc, v1
	v_lshrrev_b32_e32 v0, 1, v0
	v_or_b32_e32 v1, s73, v1
	v_and_b32_e32 v0, 0x3e0, v0
	v_lshl_or_b32 v0, v1, 10, v0
	v_ashrrev_i32_e32 v1, 31, v0
	v_lshlrev_b64 v[0:1], 10, v[0:1]
	v_lshl_add_u64 v[0:1], v[140:141], 0, v[0:1]
	v_cvt_pk_bf16_f32 v129, v124, v125
	v_cvt_pk_bf16_f32 v106, v118, v119
	v_cvt_pk_bf16_f32 v107, v120, v121
	v_cvt_pk_bf16_f32 v108, v114, v115
	v_cvt_pk_bf16_f32 v109, v116, v117
	v_cvt_pk_bf16_f32 v90, v102, v103
	v_cvt_pk_bf16_f32 v91, v104, v105
	v_cvt_pk_bf16_f32 v92, v98, v99
	v_cvt_pk_bf16_f32 v93, v100, v101
	v_cvt_pk_bf16_f32 v74, v86, v87
	v_cvt_pk_bf16_f32 v75, v88, v89
	v_cvt_pk_bf16_f32 v76, v82, v83
	v_cvt_pk_bf16_f32 v77, v84, v85
	v_cvt_pk_bf16_f32 v62, v62, v63
	v_cvt_pk_bf16_f32 v63, v64, v65
	v_cvt_pk_bf16_f32 v64, v58, v59
	v_lshl_add_u64 v[58:59], v[0:1], 0, s[8:9]
	v_cvt_pk_bf16_f32 v50, v50, v51
	v_cvt_pk_bf16_f32 v51, v52, v53
	v_cvt_pk_bf16_f32 v52, v42, v43
	v_cvt_pk_bf16_f32 v53, v44, v45
	v_lshl_add_u64 v[0:1], v[0:1], 0, s[12:13]
	global_store_dwordx4 v[122:123], v[126:129], off sc1
	global_store_dwordx4 v[110:111], v[106:109], off sc1
	global_store_dwordx4 v[94:95], v[90:93], off sc1
	global_store_dwordx4 v[78:79], v[74:77], off sc1
	global_store_dwordx4 v[0:1], v[50:53], off sc1
	v_add_u32_e32 v0, 0x90, v138
	v_lshrrev_b32_e32 v1, 9, v0
	v_and_b32_e32 v1, 0x3ffffc, v1
	v_or_b32_e32 v1, s73, v1
	v_lshrrev_b32_e32 v0, 1, v0
	v_lshlrev_b32_e32 v1, 10, v1
	v_and_b32_e32 v0, 0x3e0, v0
	v_or3_b32 v0, v1, v0, 8
	v_ashrrev_i32_e32 v1, 31, v0
	v_lshlrev_b64 v[0:1], 10, v[0:1]
	v_lshl_add_u64 v[0:1], v[140:141], 0, v[0:1]
	v_cvt_pk_bf16_f32 v65, v60, v61
	v_cvt_pk_bf16_f32 v44, v46, v47
	v_lshl_add_u64 v[46:47], v[0:1], 0, s[8:9]
	v_cvt_pk_bf16_f32 v34, v34, v35
	v_cvt_pk_bf16_f32 v35, v36, v37
	v_cvt_pk_bf16_f32 v36, v26, v27
	v_cvt_pk_bf16_f32 v37, v28, v29
	v_lshl_add_u64 v[0:1], v[0:1], 0, s[12:13]
	global_store_dwordx4 v[58:59], v[62:65], off sc1
	global_store_dwordx4 v[0:1], v[34:37], off sc1
	v_add_u32_e32 v0, 0xa0, v138
	v_lshrrev_b32_e32 v1, 9, v0
	v_and_b32_e32 v1, 0x3ffffc, v1
	v_or_b32_e32 v1, s73, v1
	v_lshrrev_b32_e32 v0, 1, v0
	v_lshlrev_b32_e32 v1, 10, v1
	v_and_b32_e32 v0, 0x3e0, v0
	v_or3_b32 v0, v1, v0, 16
	v_ashrrev_i32_e32 v1, 31, v0
	v_lshlrev_b64 v[0:1], 10, v[0:1]
	v_lshl_add_u64 v[0:1], v[140:141], 0, v[0:1]
	v_cvt_pk_bf16_f32 v42, v54, v55
	v_cvt_pk_bf16_f32 v43, v56, v57
	v_cvt_pk_bf16_f32 v45, v48, v49
	v_cvt_pk_bf16_f32 v28, v30, v31
	v_lshl_add_u64 v[30:31], v[0:1], 0, s[8:9]
	v_cvt_pk_bf16_f32 v18, v18, v19
	v_cvt_pk_bf16_f32 v19, v20, v21
	v_cvt_pk_bf16_f32 v20, v10, v11
	v_cvt_pk_bf16_f32 v21, v12, v13
	v_lshl_add_u64 v[0:1], v[0:1], 0, s[12:13]
	global_store_dwordx4 v[46:47], v[42:45], off sc1
	global_store_dwordx4 v[0:1], v[18:21], off sc1
	v_add_u32_e32 v0, 0xb0, v138
	v_lshrrev_b32_e32 v1, 9, v0
	v_and_b32_e32 v1, 0x3ffffc, v1
	v_or_b32_e32 v1, s73, v1
	v_lshrrev_b32_e32 v0, 1, v0
	v_lshlrev_b32_e32 v1, 10, v1
	v_and_b32_e32 v0, 0x3e0, v0
	v_or3_b32 v0, v1, v0, 24
	v_ashrrev_i32_e32 v1, 31, v0
	v_lshlrev_b64 v[0:1], 10, v[0:1]
	v_lshl_add_u64 v[0:1], v[140:141], 0, v[0:1]
	v_cvt_pk_bf16_f32 v26, v38, v39
	v_cvt_pk_bf16_f32 v27, v40, v41
	v_cvt_pk_bf16_f32 v29, v32, v33
	v_cvt_pk_bf16_f32 v10, v22, v23
	v_cvt_pk_bf16_f32 v11, v24, v25
	v_cvt_pk_bf16_f32 v12, v14, v15
	v_cvt_pk_bf16_f32 v13, v16, v17
	v_lshl_add_u64 v[14:15], v[0:1], 0, s[8:9]
	v_cvt_pk_bf16_f32 v6, v6, v7
	v_cvt_pk_bf16_f32 v7, v8, v9
	v_cvt_pk_bf16_f32 v8, v2, v3
	v_cvt_pk_bf16_f32 v9, v4, v5
	v_lshl_add_u64 v[0:1], v[0:1], 0, s[12:13]
	global_store_dwordx4 v[30:31], v[26:29], off sc1
	global_store_dwordx4 v[14:15], v[10:13], off sc1
	global_store_dwordx4 v[0:1], v[6:9], off sc1
	s_andn2_b64 vcc, exec, s[20:21]
	s_mov_b64 s[0:1], -1
	s_cbranch_vccnz .LBB0_517

.LBB0_1072:
	v_lshlrev_b64 v[0:1], 11, v[160:161]
	v_lshl_add_u64 v[0:1], s[8:9], 0, v[0:1]
	v_lshlrev_b32_e32 v138, 1, v145
	v_lshl_add_u64 v[0:1], v[0:1], 0, v[138:139]
	global_store_dwordx4 v[0:1], v[126:129], off sc1
	global_store_dwordx4 v[0:1], v[106:109], off offset:256 sc1
	v_lshlrev_b64 v[0:1], 11, v[158:159]
	v_lshl_add_u64 v[0:1], s[8:9], 0, v[0:1]
	v_lshl_add_u64 v[0:1], v[0:1], 0, v[138:139]
	global_store_dwordx4 v[0:1], v[98:101], off sc1
	global_store_dwordx4 v[0:1], v[90:93], off offset:256 sc1
	v_lshlrev_b64 v[0:1], 11, v[156:157]
	v_lshl_add_u64 v[0:1], s[8:9], 0, v[0:1]
	v_lshl_add_u64 v[0:1], v[0:1], 0, v[138:139]
	global_store_dwordx4 v[0:1], v[82:85], off sc1
	global_store_dwordx4 v[0:1], v[78:81], off offset:256 sc1
	v_lshlrev_b64 v[0:1], 11, v[154:155]
	v_lshl_add_u64 v[0:1], s[8:9], 0, v[0:1]
	v_lshl_add_u64 v[0:1], v[0:1], 0, v[138:139]
	global_store_dwordx4 v[0:1], v[74:77], off sc1
	global_store_dwordx4 v[0:1], v[70:73], off offset:256 sc1
	v_lshlrev_b64 v[0:1], 11, v[152:153]
	v_lshl_add_u64 v[0:1], s[8:9], 0, v[0:1]
	v_lshl_add_u64 v[0:1], v[0:1], 0, v[138:139]
	global_store_dwordx4 v[0:1], v[62:65], off sc1
	global_store_dwordx4 v[0:1], v[42:45], off offset:256 sc1
	v_lshlrev_b64 v[0:1], 11, v[150:151]
	v_lshl_add_u64 v[0:1], s[8:9], 0, v[0:1]
	v_lshl_add_u64 v[0:1], v[0:1], 0, v[138:139]
	global_store_dwordx4 v[0:1], v[34:37], off sc1
	global_store_dwordx4 v[0:1], v[26:29], off offset:256 sc1
	v_lshlrev_b64 v[0:1], 11, v[148:149]
	v_lshl_add_u64 v[0:1], s[8:9], 0, v[0:1]
	v_lshl_add_u64 v[0:1], v[0:1], 0, v[138:139]
	global_store_dwordx4 v[0:1], v[18:21], off sc1
	global_store_dwordx4 v[0:1], v[14:17], off offset:256 sc1
	v_lshlrev_b64 v[0:1], 11, v[146:147]
	v_lshl_add_u64 v[0:1], s[8:9], 0, v[0:1]
	v_lshl_add_u64 v[0:1], v[0:1], 0, v[138:139]
	global_store_dwordx4 v[0:1], v[10:13], off sc1
	global_store_dwordx4 v[0:1], v[6:9], off offset:256 sc1
	s_cbranch_execnz .LBB0_1071
.LBB0_1073:
	v_lshlrev_b32_e32 v2, 15, v145
	v_and_b32_e32 v138, 0x1b80000, v2
	v_lshlrev_b64 v[0:1], 5, v[160:161]
	v_lshl_add_u64 v[2:3], s[6:7], 0, v[138:139]
	v_lshl_add_u64 v[4:5], v[2:3], 0, v[0:1]
	v_mov_b32_e32 v145, v139
	v_lshl_add_u64 v[4:5], v[4:5], 0, v[144:145]
	s_mov_b64 s[0:1], 0x400000
	global_store_dwordx4 v[4:5], v[126:129], off sc1
	v_lshl_add_u64 v[4:5], v[2:3], 0, s[0:1]
	v_lshl_add_u64 v[0:1], v[4:5], 0, v[0:1]
	v_lshl_add_u64 v[0:1], v[0:1], 0, v[144:145]
	global_store_dwordx4 v[0:1], v[106:109], off sc1
	v_lshlrev_b64 v[0:1], 5, v[158:159]
	v_lshl_add_u64 v[22:23], v[2:3], 0, v[0:1]
	v_lshl_add_u64 v[0:1], v[4:5], 0, v[0:1]
	v_lshl_add_u64 v[0:1], v[0:1], 0, v[144:145]
	v_lshl_add_u64 v[22:23], v[22:23], 0, v[144:145]
	global_store_dwordx4 v[0:1], v[90:93], off sc1
	v_lshlrev_b64 v[0:1], 5, v[156:157]
	global_store_dwordx4 v[22:23], v[98:101], off sc1
	v_lshl_add_u64 v[22:23], v[2:3], 0, v[0:1]
	v_lshl_add_u64 v[0:1], v[4:5], 0, v[0:1]
	v_lshl_add_u64 v[0:1], v[0:1], 0, v[144:145]
	v_lshl_add_u64 v[22:23], v[22:23], 0, v[144:145]
	global_store_dwordx4 v[0:1], v[78:81], off sc1
	v_lshlrev_b64 v[0:1], 5, v[154:155]
	global_store_dwordx4 v[22:23], v[82:85], off sc1
	v_lshl_add_u64 v[22:23], v[2:3], 0, v[0:1]
	v_lshl_add_u64 v[0:1], v[4:5], 0, v[0:1]
	v_lshl_add_u64 v[0:1], v[0:1], 0, v[144:145]
	v_lshl_add_u64 v[22:23], v[22:23], 0, v[144:145]
	global_store_dwordx4 v[0:1], v[70:73], off sc1
	v_lshlrev_b64 v[0:1], 5, v[152:153]
	global_store_dwordx4 v[22:23], v[74:77], off sc1
	v_lshl_add_u64 v[22:23], v[2:3], 0, v[0:1]
	v_lshl_add_u64 v[0:1], v[4:5], 0, v[0:1]
	v_lshl_add_u64 v[0:1], v[0:1], 0, v[144:145]
	v_lshl_add_u64 v[22:23], v[22:23], 0, v[144:145]
	global_store_dwordx4 v[0:1], v[42:45], off sc1
	v_lshlrev_b64 v[0:1], 5, v[150:151]
	global_store_dwordx4 v[22:23], v[62:65], off sc1
	v_lshl_add_u64 v[22:23], v[2:3], 0, v[0:1]
	v_lshl_add_u64 v[0:1], v[4:5], 0, v[0:1]
	v_lshl_add_u64 v[0:1], v[0:1], 0, v[144:145]
	v_lshl_add_u64 v[22:23], v[22:23], 0, v[144:145]
	global_store_dwordx4 v[0:1], v[26:29], off sc1
	v_lshlrev_b64 v[0:1], 5, v[148:149]
	global_store_dwordx4 v[22:23], v[34:37], off sc1
	v_lshl_add_u64 v[22:23], v[2:3], 0, v[0:1]
	v_lshl_add_u64 v[0:1], v[4:5], 0, v[0:1]
	v_lshl_add_u64 v[0:1], v[0:1], 0, v[144:145]
	global_store_dwordx4 v[0:1], v[14:17], off sc1
	v_lshlrev_b64 v[0:1], 5, v[146:147]
	v_lshl_add_u64 v[2:3], v[2:3], 0, v[0:1]
	v_lshl_add_u64 v[0:1], v[4:5], 0, v[0:1]
	v_lshl_add_u64 v[22:23], v[22:23], 0, v[144:145]
	v_lshl_add_u64 v[2:3], v[2:3], 0, v[144:145]
	v_lshl_add_u64 v[0:1], v[0:1], 0, v[144:145]
	global_store_dwordx4 v[22:23], v[18:21], off sc1
	global_store_dwordx4 v[2:3], v[10:13], off sc1
	global_store_dwordx4 v[0:1], v[6:9], off sc1
	s_andn2_b64 vcc, exec, s[20:21]
	s_mov_b64 s[0:1], -1
	s_cbranch_vccnz .LBB0_1062

; DEV float siluf_(float x) { return x * __builtin_amdgcn_rcpf(1.f + __expf(-x)); }
; #define LAS __attribute__((address_space(3)))
; DEV uint4 pack8(const float* f) { return make_uint4(pk2(f[0], f[1]), pk2(f[2], f[3]), pk2(f[4], f[5]), pk2(f[6], f[7])); }
; DEV void xc_gates_phase(LAS char* shm, const bf16_t* mi, bf16_t* xc, const bf16_t* WfT, const float* cw, const float* cb, float* gpart  ) {
;     ...
;         auto compute = [&](int c0) {
; #pragma nounroll
;             for (int ks = 0; ks < 4; ++ks) {
;                 const int cl = 32 * ks + 8 * fq, c = c0 + cl;
;                 float xv[8], t8[8];
;                 { const f32x4 b0 = *(const LAS f32x4*)(shm + CWL + 16384 + c * 4), b1 = *(const LAS f32x4*)(shm + CWL + 16384 + c * 4 + 16);
;                   xv[0] = b0[0]; xv[1] = b0[1]; xv[2] = b0[2]; xv[3] = b0[3]; xv[4] = b1[0]; xv[5] = b1[1]; xv[6] = b1[2]; xv[7] = b1[3]; }
;                 u32x4 raw3;
; #pragma unroll
;                 for (int tap = 0; tap < 4; ++tap) {
;                     const u32x4 rw = *(const LAS u32x4*)(stg + (fr + tap) * SRS_ + cl * 2);
;                     if (tap == 3) raw3 = rw;
;                     unpack8(make_uint4(rw[0], rw[1], rw[2], rw[3]), t8);
;                     const f32x4 w0 = *(const LAS f32x4*)(shm + CWL + tap * 4096 + c * 4), w1 = *(const LAS f32x4*)(shm + CWL + tap * 4096 + c * 4 + 16);
;                     xv[0] += t8[0] * w0[0]; xv[1] += t8[1] * w0[1]; xv[2] += t8[2] * w0[2]; xv[3] += t8[3] * w0[3];
;                     xv[4] += t8[4] * w1[0]; xv[5] += t8[5] * w1[1]; xv[6] += t8[6] * w1[2]; xv[7] += t8[7] * w1[3];
;                 }
; #pragma unroll
;                 for (int e = 0; e < 8; ++e) xv[e] = siluf_(xv[e]);
;                 const uint4 xp = pack8(xv);
;                 *(uint4*)(xc + (size_t)(m0 + fr) * DM + c) = xp;
;                 const u32x4 xpu = (u32x4){xp.x, xp.y, xp.z, xp.w};
;                 const bf16x8 bx = *(const LAS bf16x8*)(shm + (fr & 7) * WRS + c * 2);
;                 const bf16x8 bv = *(const LAS bf16x8*)(shm + WIMG + (fr & 7) * WRS + c * 2);
;                 acc = __builtin_amdgcn_mfma_f32_16x16x32_bf16(*(const bf16x8*)&xpu, bx, acc, 0, 0, 0);
;                 acc = __builtin_amdgcn_mfma_f32_16x16x32_bf16(*(const bf16x8*)&raw3, bv, acc, 0, 0, 0);
;             }
.LBB0_1213:
	ds_read_b128 v[90:93], v5 offset:16384
	ds_read_b128 v[94:97], v5 offset:16400
	ds_read_b128 v[98:101], v5
	ds_read_b128 v[102:105], v5 offset:16
	ds_read_b128 v[106:109], v89
	ds_read_b128 v[110:113], v89 offset:528
	ds_read_b128 v[114:117], v5 offset:4096
	ds_read_b128 v[118:121], v5 offset:4112
	ds_read_b128 v[122:125], v5 offset:8192
	ds_read_b128 v[126:129], v5 offset:8208
	ds_read_b128 v[130:133], v89 offset:1056
	ds_read_b128 v[50:53], v89 offset:1584
	ds_read_b128 v[134:137], v5 offset:12288
	ds_read_b128 v[138:141], v5 offset:12304
	s_waitcnt lgkmcnt(9)
	v_lshlrev_b32_e32 v150, 16, v106
	v_and_b32_e32 v151, 0xffff0000, v106
	v_lshlrev_b32_e32 v106, 16, v107
	v_and_b32_e32 v107, 0xffff0000, v107
	v_lshlrev_b32_e32 v160, 16, v108
	v_and_b32_e32 v161, 0xffff0000, v108
	v_lshlrev_b32_e32 v108, 16, v109
	v_and_b32_e32 v109, 0xffff0000, v109
	s_waitcnt lgkmcnt(8)
	v_lshlrev_b32_e32 v152, 16, v110
	v_and_b32_e32 v153, 0xffff0000, v110
	v_lshlrev_b32_e32 v110, 16, v111
	v_and_b32_e32 v111, 0xffff0000, v111
	v_lshlrev_b32_e32 v162, 16, v112
	v_and_b32_e32 v163, 0xffff0000, v112
	v_lshlrev_b32_e32 v112, 16, v113
	v_and_b32_e32 v113, 0xffff0000, v113
	v_pk_fma_f32 v[90:91], v[98:99], v[150:151], v[90:91]
	v_pk_fma_f32 v[92:93], v[100:101], v[106:107], v[92:93]
	v_pk_fma_f32 v[94:95], v[102:103], v[160:161], v[94:95]
	v_pk_fma_f32 v[96:97], v[104:105], v[108:109], v[96:97]
	s_waitcnt lgkmcnt(3)
	v_lshlrev_b32_e32 v154, 16, v130
	v_and_b32_e32 v155, 0xffff0000, v130
	v_lshlrev_b32_e32 v130, 16, v131
	v_and_b32_e32 v131, 0xffff0000, v131
	v_lshlrev_b32_e32 v164, 16, v132
	v_and_b32_e32 v165, 0xffff0000, v132
	v_lshlrev_b32_e32 v132, 16, v133
	v_and_b32_e32 v133, 0xffff0000, v133
	v_pk_fma_f32 v[90:91], v[114:115], v[152:153], v[90:91]
	v_pk_fma_f32 v[92:93], v[116:117], v[110:111], v[92:93]
	v_pk_fma_f32 v[94:95], v[118:119], v[162:163], v[94:95]
	v_pk_fma_f32 v[96:97], v[120:121], v[112:113], v[96:97]
	s_waitcnt lgkmcnt(2)
	v_lshlrev_b32_e32 v156, 16, v50
	v_and_b32_e32 v157, 0xffff0000, v50
	v_lshlrev_b32_e32 v158, 16, v51
	v_and_b32_e32 v159, 0xffff0000, v51
	v_lshlrev_b32_e32 v166, 16, v52
	v_and_b32_e32 v167, 0xffff0000, v52
	v_lshlrev_b32_e32 v168, 16, v53
	v_and_b32_e32 v169, 0xffff0000, v53
	v_pk_fma_f32 v[90:91], v[122:123], v[154:155], v[90:91]
	v_pk_fma_f32 v[92:93], v[124:125], v[130:131], v[92:93]
	v_pk_fma_f32 v[94:95], v[126:127], v[164:165], v[94:95]
	v_pk_fma_f32 v[96:97], v[128:129], v[132:133], v[96:97]
	s_waitcnt lgkmcnt(1)
	v_pk_fma_f32 v[90:91], v[134:135], v[156:157], v[90:91]
	v_pk_fma_f32 v[92:93], v[136:137], v[158:159], v[92:93]
	s_waitcnt lgkmcnt(0)
	v_pk_fma_f32 v[94:95], v[138:139], v[166:167], v[94:95]
	v_pk_fma_f32 v[96:97], v[140:141], v[168:169], v[96:97]
	v_mul_f32_e32 v98, 0xbfb8aa3b, v90
	v_mul_f32_e32 v99, 0xbfb8aa3b, v91
	v_mul_f32_e32 v100, 0xbfb8aa3b, v92
	v_mul_f32_e32 v101, 0xbfb8aa3b, v93
	v_mul_f32_e32 v102, 0xbfb8aa3b, v94
	v_mul_f32_e32 v103, 0xbfb8aa3b, v95
	v_mul_f32_e32 v104, 0xbfb8aa3b, v96
	v_mul_f32_e32 v105, 0xbfb8aa3b, v97
	v_exp_f32_e32 v98, v98
	v_exp_f32_e32 v99, v99
	v_exp_f32_e32 v100, v100
	v_exp_f32_e32 v101, v101
	v_exp_f32_e32 v102, v102
	v_exp_f32_e32 v103, v103
	v_exp_f32_e32 v104, v104
	v_exp_f32_e32 v105, v105
	v_add_f32_e32 v98, 1.0, v98
	v_add_f32_e32 v99, 1.0, v99
	v_add_f32_e32 v100, 1.0, v100
	v_add_f32_e32 v101, 1.0, v101
	v_add_f32_e32 v102, 1.0, v102
	v_add_f32_e32 v103, 1.0, v103
	v_add_f32_e32 v104, 1.0, v104
	v_add_f32_e32 v105, 1.0, v105
	v_rcp_f32_e32 v98, v98
	v_rcp_f32_e32 v99, v99
	v_rcp_f32_e32 v100, v100
	v_rcp_f32_e32 v101, v101
	v_rcp_f32_e32 v102, v102
	v_rcp_f32_e32 v103, v103
	v_rcp_f32_e32 v104, v104
	v_rcp_f32_e32 v105, v105
	v_pk_mul_f32 v[90:91], v[90:91], v[98:99]
	v_pk_mul_f32 v[92:93], v[92:93], v[100:101]
	v_pk_mul_f32 v[94:95], v[94:95], v[102:103]
	v_pk_mul_f32 v[96:97], v[96:97], v[104:105]
	v_cvt_pk_bf16_f32 v90, v90, v91
	v_cvt_pk_bf16_f32 v91, v92, v93
	v_cvt_pk_bf16_f32 v92, v94, v95
	v_cvt_pk_bf16_f32 v93, v96, v97
	ds_read_b128 v[142:145], v3
	ds_read_b128 v[146:149], v3 offset:16512
	s_waitcnt lgkmcnt(1)
	v_mfma_f32_16x16x32_bf16 v[38:41], v[90:93], v[142:145], v[38:41]
	v_lshl_add_u64 v[0:1], v[74:75], 0, s[26:27]
	s_add_u32 s26, s26, 64
	v_add_co_u32_e32 v0, vcc, s31, v0
	s_waitcnt lgkmcnt(0)
	v_mfma_f32_16x16x32_bf16 v[38:41], v[50:53], v[146:149], v[38:41]
	s_addc_u32 s27, s27, 0
	v_add_u32_e32 v89, 64, v89
	v_add_u32_e32 v3, 64, v3
	v_add_u32_e32 v5, 0x80, v5
	v_addc_co_u32_e32 v1, vcc, 0, v1, vcc
	s_cmpk_eq_i32 s26, 0x100
	global_store_dwordx4 v[0:1], v[90:93], off sc1
	s_cbranch_scc0 .LBB0_1213
	ds_write_b128 v87, v[18:21] offset:53504
	ds_write_b128 v87, v[26:29] offset:55616
	ds_write_b128 v87, v[34:37] offset:57728
	ds_write_b128 v87, v[42:45] offset:59840
	s_and_saveexec_b64 s[0:1], s[6:7]
	ds_write_b128 v88, v[46:49] offset:53504
	s_or_b64 exec, exec, s[0:1]
	s_and_b64 vcc, exec, s[24:25]
	s_cbranch_vccz .LBB0_1228
	v_mov_b32_e32 v28, v2
	v_mov_b32_e32 v29, v2
	v_mov_b64_e32 v[20:21], v[28:29]
	v_mov_b64_e32 v[18:19], v[28:29]
	s_and_saveexec_b64 s[0:1], s[8:9]
	s_cbranch_execz .LBB0_1219
	global_load_dwordx4 v[18:21], v[64:65], off offset:768

; DEV void xc_gates_phase(LAS char* shm, const bf16_t* mi, bf16_t* xc, const bf16_t* WfT, const float* cw, const float* cb, float* gpart  ) {
;     ...
;             for (int ks = 0; ks < 4; ++ks) {
;                 const int cl = 32 * ks + 8 * fq, c = c0 + cl;
;                 float xv[8], t8[8];
;                 { const f32x4 b0 = *(const LAS f32x4*)(shm + CWL + 16384 + c * 4), b1 = *(const LAS f32x4*)(shm + CWL + 16384 + c * 4 + 16);
;                   xv[0] = b0[0]; xv[1] = b0[1]; xv[2] = b0[2]; xv[3] = b0[3]; xv[4] = b1[0]; xv[5] = b1[1]; xv[6] = b1[2]; xv[7] = b1[3]; }
;                 u32x4 raw3;
; #pragma unroll
;                 for (int tap = 0; tap < 4; ++tap) {
;                     const u32x4 rw = *(const LAS u32x4*)(stg + (fr + tap) * SRS_ + cl * 2);
;                     if (tap == 3) raw3 = rw;
;                     unpack8(make_uint4(rw[0], rw[1], rw[2], rw[3]), t8);
;                     const f32x4 w0 = *(const LAS f32x4*)(shm + CWL + tap * 4096 + c * 4), w1 = *(const LAS f32x4*)(shm + CWL + tap * 4096 + c * 4 + 16);
;                     xv[0] += t8[0] * w0[0]; xv[1] += t8[1] * w0[1]; xv[2] += t8[2] * w0[2]; xv[3] += t8[3] * w0[3];
;                     xv[4] += t8[4] * w1[0]; xv[5] += t8[5] * w1[1]; xv[6] += t8[6] * w1[2]; xv[7] += t8[7] * w1[3];
;                 }
; #pragma unroll
;                 for (int e = 0; e < 8; ++e) xv[e] = siluf_(xv[e]);
;                 const uint4 xp = pack8(xv);
;                 *(uint4*)(xc + (size_t)(m0 + fr) * DM + c) = xp;
;                 const u32x4 xpu = (u32x4){xp.x, xp.y, xp.z, xp.w};
;                 const bf16x8 bx = *(const LAS bf16x8*)(shm + (fr & 7) * WRS + c * 2);
;                 const bf16x8 bv = *(const LAS bf16x8*)(shm + WIMG + (fr & 7) * WRS + c * 2);
;                 acc = __builtin_amdgcn_mfma_f32_16x16x32_bf16(*(const bf16x8*)&xpu, bx, acc, 0, 0, 0);
;                 acc = __builtin_amdgcn_mfma_f32_16x16x32_bf16(*(const bf16x8*)&raw3, bv, acc, 0, 0, 0);
;             }
;         };
;         XC_LOAD(pr0, 0); XC_LOAD(pr1, 1);
; #pragma nounroll
;         for (int sp = 0; sp < 2; ++sp) {
;             XC_STAGE(pr0); if (sp == 0) XC_LOAD(pr0, 2);
;             compute(chalf * 512 + (2 * sp) * 128);
;             XC_STAGE(pr1); if (sp == 0) XC_LOAD(pr1, 3);
;             compute(chalf * 512 + (2 * sp + 1) * 128);
;         }
;     ...
;         if (fr < 8) {
; #pragma unroll
.LBB0_1229:
	ds_read_b128 v[90:93], v74 offset:16384
	ds_read_b128 v[94:97], v74 offset:16400
	ds_read_b128 v[98:101], v74
	ds_read_b128 v[102:105], v74 offset:16
	ds_read_b128 v[106:109], v75
	ds_read_b128 v[110:113], v75 offset:528
	ds_read_b128 v[114:117], v74 offset:4096
	ds_read_b128 v[118:121], v74 offset:4112
	ds_read_b128 v[122:125], v74 offset:8192
	ds_read_b128 v[126:129], v74 offset:8208
	ds_read_b128 v[130:133], v75 offset:1056
	ds_read_b128 v[50:53], v75 offset:1584
	ds_read_b128 v[134:137], v74 offset:12288
	ds_read_b128 v[138:141], v74 offset:12304
	s_waitcnt lgkmcnt(9)
	v_lshlrev_b32_e32 v150, 16, v106
	v_and_b32_e32 v151, 0xffff0000, v106
	v_lshlrev_b32_e32 v106, 16, v107
	v_and_b32_e32 v107, 0xffff0000, v107
	v_lshlrev_b32_e32 v160, 16, v108
	v_and_b32_e32 v161, 0xffff0000, v108
	v_lshlrev_b32_e32 v108, 16, v109
	v_and_b32_e32 v109, 0xffff0000, v109
	s_waitcnt lgkmcnt(8)
	v_lshlrev_b32_e32 v152, 16, v110
	v_and_b32_e32 v153, 0xffff0000, v110
	v_lshlrev_b32_e32 v110, 16, v111
	v_and_b32_e32 v111, 0xffff0000, v111
	v_lshlrev_b32_e32 v162, 16, v112
	v_and_b32_e32 v163, 0xffff0000, v112
	v_lshlrev_b32_e32 v112, 16, v113
	v_and_b32_e32 v113, 0xffff0000, v113
	v_pk_fma_f32 v[90:91], v[98:99], v[150:151], v[90:91]
	v_pk_fma_f32 v[92:93], v[100:101], v[106:107], v[92:93]
	v_pk_fma_f32 v[94:95], v[102:103], v[160:161], v[94:95]
	v_pk_fma_f32 v[96:97], v[104:105], v[108:109], v[96:97]
	s_waitcnt lgkmcnt(3)
	v_lshlrev_b32_e32 v154, 16, v130
	v_and_b32_e32 v155, 0xffff0000, v130
	v_lshlrev_b32_e32 v130, 16, v131
	v_and_b32_e32 v131, 0xffff0000, v131
	v_lshlrev_b32_e32 v164, 16, v132
	v_and_b32_e32 v165, 0xffff0000, v132
	v_lshlrev_b32_e32 v132, 16, v133
	v_and_b32_e32 v133, 0xffff0000, v133
	v_pk_fma_f32 v[90:91], v[114:115], v[152:153], v[90:91]
	v_pk_fma_f32 v[92:93], v[116:117], v[110:111], v[92:93]
	v_pk_fma_f32 v[94:95], v[118:119], v[162:163], v[94:95]
	v_pk_fma_f32 v[96:97], v[120:121], v[112:113], v[96:97]
	s_waitcnt lgkmcnt(2)
	v_lshlrev_b32_e32 v156, 16, v50
	v_and_b32_e32 v157, 0xffff0000, v50
	v_lshlrev_b32_e32 v158, 16, v51
	v_and_b32_e32 v159, 0xffff0000, v51
	v_lshlrev_b32_e32 v166, 16, v52
	v_and_b32_e32 v167, 0xffff0000, v52
	v_lshlrev_b32_e32 v168, 16, v53
	v_and_b32_e32 v169, 0xffff0000, v53
	v_pk_fma_f32 v[90:91], v[122:123], v[154:155], v[90:91]
	v_pk_fma_f32 v[92:93], v[124:125], v[130:131], v[92:93]
	v_pk_fma_f32 v[94:95], v[126:127], v[164:165], v[94:95]
	v_pk_fma_f32 v[96:97], v[128:129], v[132:133], v[96:97]
	s_waitcnt lgkmcnt(1)
	v_pk_fma_f32 v[90:91], v[134:135], v[156:157], v[90:91]
	v_pk_fma_f32 v[92:93], v[136:137], v[158:159], v[92:93]
	s_waitcnt lgkmcnt(0)
	v_pk_fma_f32 v[94:95], v[138:139], v[166:167], v[94:95]
	v_pk_fma_f32 v[96:97], v[140:141], v[168:169], v[96:97]
	v_mul_f32_e32 v89, 0xbfb8aa3b, v90
	v_mul_f32_e32 v98, 0xbfb8aa3b, v91
	v_mul_f32_e32 v99, 0xbfb8aa3b, v92
	v_mul_f32_e32 v100, 0xbfb8aa3b, v93
	v_mul_f32_e32 v101, 0xbfb8aa3b, v94
	v_mul_f32_e32 v102, 0xbfb8aa3b, v95
	v_mul_f32_e32 v103, 0xbfb8aa3b, v96
	v_mul_f32_e32 v104, 0xbfb8aa3b, v97
	v_exp_f32_e32 v89, v89
	v_exp_f32_e32 v98, v98
	v_exp_f32_e32 v99, v99
	v_exp_f32_e32 v100, v100
	v_exp_f32_e32 v101, v101
	v_exp_f32_e32 v102, v102
	v_exp_f32_e32 v103, v103
	v_exp_f32_e32 v104, v104
	v_add_f32_e32 v89, 1.0, v89
	v_add_f32_e32 v105, 1.0, v98
	v_add_f32_e32 v106, 1.0, v99
	v_add_f32_e32 v107, 1.0, v100
	v_add_f32_e32 v108, 1.0, v101
	v_add_f32_e32 v109, 1.0, v102
	v_add_f32_e32 v110, 1.0, v103
	v_add_f32_e32 v111, 1.0, v104
	v_rcp_f32_e32 v98, v89
	v_rcp_f32_e32 v99, v105
	v_rcp_f32_e32 v100, v106
	v_rcp_f32_e32 v101, v107
	v_rcp_f32_e32 v102, v108
	v_rcp_f32_e32 v103, v109
	v_rcp_f32_e32 v104, v110
	v_rcp_f32_e32 v105, v111
	v_pk_mul_f32 v[90:91], v[90:91], v[98:99]
	v_pk_mul_f32 v[92:93], v[92:93], v[100:101]
	v_pk_mul_f32 v[94:95], v[94:95], v[102:103]
	v_pk_mul_f32 v[96:97], v[96:97], v[104:105]
	v_cvt_pk_bf16_f32 v90, v90, v91
	v_cvt_pk_bf16_f32 v91, v92, v93
	v_cvt_pk_bf16_f32 v92, v94, v95
	v_cvt_pk_bf16_f32 v93, v96, v97
	ds_read_b128 v[142:145], v3
	ds_read_b128 v[146:149], v3 offset:16512
	s_waitcnt lgkmcnt(1)
	v_mfma_f32_16x16x32_bf16 v[38:41], v[90:93], v[142:145], v[38:41]
	v_lshl_add_u64 v[0:1], v[4:5], 0, s[24:25]
	s_add_u32 s24, s24, 64
	v_add_co_u32_e32 v0, vcc, s31, v0
	s_waitcnt lgkmcnt(0)
	v_mfma_f32_16x16x32_bf16 v[38:41], v[50:53], v[146:149], v[38:41]
	s_addc_u32 s25, s25, 0
	v_add_u32_e32 v75, 64, v75
	v_add_u32_e32 v3, 64, v3
	v_add_u32_e32 v74, 0x80, v74
	v_addc_co_u32_e32 v1, vcc, 0, v1, vcc
	s_cmpk_lg_i32 s24, 0x100
	global_store_dwordx4 v[0:1], v[90:93], off offset:256 sc1
	s_cbranch_scc1 .LBB0_1229
	s_movk_i32 s19, 0x100
	s_mov_b64 s[24:25], 0
	s_and_b64 vcc, exec, s[22:23]
	s_cbranch_vccz .LBB0_1198
	s_and_saveexec_b64 s[0:1], s[4:5]
	s_cbranch_execz .LBB0_1176
	s_ashr_i32 s19, s18, 31
	v_lshl_add_u64 v[0:1], s[18:19], 0, v[58:59]
	v_lshlrev_b64 v[0:1], 5, v[0:1]
	v_lshl_add_u64 v[0:1], v[54:55], 0, v[0:1]
	global_store_dword v[0:1], v38, off
	global_store_dword v[0:1], v39, off offset:32
	global_store_dword v[0:1], v40, off offset:64
	global_store_dword v[0:1], v41, off offset:96
	s_branch .LBB0_1176

.LBB0_1379:
	s_cmp_lt_u32 s64, 8
	s_cselect_b64 vcc, -1, 0
	s_and_b64 s[0:1], vcc, exec
	s_cselect_b32 s1, s61, s66
	s_cselect_b32 s0, s60, s65
	s_lshl_b32 s13, s64, 8
	s_and_b32 s13, s13, 0x300
	v_or_b32_e32 v0, s13, v150
	v_lshl_add_u32 v146, s80, 8, v148
	v_cndmask_b32_e32 v142, 1.0, v154, vcc
	v_lshlrev_b32_e32 v138, 1, v0
	v_ashrrev_i32_e32 v147, 31, v146
	v_lshl_add_u64 v[144:145], s[0:1], 0, v[138:139]
	v_lshlrev_b64 v[0:1], 11, v[146:147]
	v_pk_mul_f32 v[158:159], v[142:143], v[128:129] op_sel_hi:[0,1]
	v_pk_mul_f32 v[156:157], v[142:143], v[126:127] op_sel_hi:[0,1]
	v_pk_mul_f32 v[160:161], v[142:143], v[124:125] op_sel_hi:[0,1]
	v_pk_mul_f32 v[162:163], v[142:143], v[122:123] op_sel_hi:[0,1]
	v_lshl_add_u64 v[0:1], v[144:145], 0, v[0:1]
	v_cvt_pk_bf16_f32 v156, v156, v157
	v_cvt_pk_bf16_f32 v157, v158, v159
	v_cvt_pk_bf16_f32 v158, v162, v163
	v_cvt_pk_bf16_f32 v159, v160, v161
	global_store_dwordx4 v[0:1], v[156:159], off sc1
	v_pk_mul_f32 v[160:161], v[142:143], v[108:109] op_sel_hi:[0,1]
	v_pk_mul_f32 v[162:163], v[142:143], v[106:107] op_sel_hi:[0,1]
	v_pk_mul_f32 v[158:159], v[142:143], v[112:113] op_sel_hi:[0,1]
	v_pk_mul_f32 v[156:157], v[142:143], v[110:111] op_sel_hi:[0,1]
	v_cvt_pk_bf16_f32 v156, v156, v157
	v_cvt_pk_bf16_f32 v157, v158, v159
	v_cvt_pk_bf16_f32 v158, v162, v163
	v_cvt_pk_bf16_f32 v159, v160, v161
	global_store_dwordx4 v[0:1], v[156:159], off offset:256 sc1
	v_or_b32_e32 v0, 16, v146
	v_ashrrev_i32_e32 v1, 31, v0
	v_lshlrev_b64 v[0:1], 11, v[0:1]
	v_pk_mul_f32 v[158:159], v[142:143], v[120:121] op_sel_hi:[0,1]
	v_pk_mul_f32 v[156:157], v[142:143], v[118:119] op_sel_hi:[0,1]
	v_pk_mul_f32 v[160:161], v[142:143], v[116:117] op_sel_hi:[0,1]
	v_pk_mul_f32 v[162:163], v[142:143], v[114:115] op_sel_hi:[0,1]
	v_lshl_add_u64 v[0:1], v[144:145], 0, v[0:1]
	v_cvt_pk_bf16_f32 v156, v156, v157
	v_cvt_pk_bf16_f32 v157, v158, v159
	v_cvt_pk_bf16_f32 v158, v162, v163
	v_cvt_pk_bf16_f32 v159, v160, v161
	global_store_dwordx4 v[0:1], v[156:159], off sc1
	v_pk_mul_f32 v[160:161], v[142:143], v[92:93] op_sel_hi:[0,1]
	v_pk_mul_f32 v[162:163], v[142:143], v[90:91] op_sel_hi:[0,1]
	v_pk_mul_f32 v[158:159], v[142:143], v[96:97] op_sel_hi:[0,1]
	v_pk_mul_f32 v[156:157], v[142:143], v[94:95] op_sel_hi:[0,1]
	v_cvt_pk_bf16_f32 v156, v156, v157
	v_cvt_pk_bf16_f32 v157, v158, v159
	v_cvt_pk_bf16_f32 v158, v162, v163
	v_cvt_pk_bf16_f32 v159, v160, v161
	global_store_dwordx4 v[0:1], v[156:159], off offset:256 sc1
	v_or_b32_e32 v0, 32, v146
	v_ashrrev_i32_e32 v1, 31, v0
	v_lshlrev_b64 v[0:1], 11, v[0:1]
	v_pk_mul_f32 v[158:159], v[142:143], v[104:105] op_sel_hi:[0,1]
	v_pk_mul_f32 v[156:157], v[142:143], v[102:103] op_sel_hi:[0,1]
	v_pk_mul_f32 v[160:161], v[142:143], v[100:101] op_sel_hi:[0,1]
	v_pk_mul_f32 v[162:163], v[142:143], v[98:99] op_sel_hi:[0,1]
	v_lshl_add_u64 v[0:1], v[144:145], 0, v[0:1]
	v_cvt_pk_bf16_f32 v156, v156, v157
	v_cvt_pk_bf16_f32 v157, v158, v159
	v_cvt_pk_bf16_f32 v158, v162, v163
	v_cvt_pk_bf16_f32 v159, v160, v161
	global_store_dwordx4 v[0:1], v[156:159], off sc1
	v_pk_mul_f32 v[160:161], v[142:143], v[76:77] op_sel_hi:[0,1]
	v_pk_mul_f32 v[162:163], v[142:143], v[74:75] op_sel_hi:[0,1]
	v_pk_mul_f32 v[158:159], v[142:143], v[80:81] op_sel_hi:[0,1]
	v_pk_mul_f32 v[156:157], v[142:143], v[78:79] op_sel_hi:[0,1]
	v_cvt_pk_bf16_f32 v156, v156, v157
	v_cvt_pk_bf16_f32 v157, v158, v159
	v_cvt_pk_bf16_f32 v158, v162, v163
	v_cvt_pk_bf16_f32 v159, v160, v161
	global_store_dwordx4 v[0:1], v[156:159], off offset:256 sc1
	v_or_b32_e32 v0, 48, v146
	v_ashrrev_i32_e32 v1, 31, v0
	v_lshlrev_b64 v[0:1], 11, v[0:1]
	v_pk_mul_f32 v[158:159], v[142:143], v[88:89] op_sel_hi:[0,1]
	v_pk_mul_f32 v[156:157], v[142:143], v[86:87] op_sel_hi:[0,1]
	v_pk_mul_f32 v[160:161], v[142:143], v[84:85] op_sel_hi:[0,1]
	v_pk_mul_f32 v[162:163], v[142:143], v[82:83] op_sel_hi:[0,1]
	v_lshl_add_u64 v[0:1], v[144:145], 0, v[0:1]
	v_cvt_pk_bf16_f32 v156, v156, v157
	v_cvt_pk_bf16_f32 v157, v158, v159
	v_cvt_pk_bf16_f32 v158, v162, v163
	v_cvt_pk_bf16_f32 v159, v160, v161
	global_store_dwordx4 v[0:1], v[156:159], off sc1
	v_pk_mul_f32 v[160:161], v[142:143], v[68:69] op_sel_hi:[0,1]
	v_pk_mul_f32 v[162:163], v[142:143], v[66:67] op_sel_hi:[0,1]
	v_pk_mul_f32 v[158:159], v[142:143], v[72:73] op_sel_hi:[0,1]
	v_pk_mul_f32 v[156:157], v[142:143], v[70:71] op_sel_hi:[0,1]
	v_cvt_pk_bf16_f32 v156, v156, v157
	v_cvt_pk_bf16_f32 v157, v158, v159
	v_cvt_pk_bf16_f32 v158, v162, v163
	v_cvt_pk_bf16_f32 v159, v160, v161
	global_store_dwordx4 v[0:1], v[156:159], off offset:256 sc1
	v_add_u32_e32 v0, 0x80, v146
	v_ashrrev_i32_e32 v1, 31, v0
	v_lshlrev_b64 v[0:1], 11, v[0:1]
	v_pk_mul_f32 v[158:159], v[142:143], v[64:65] op_sel_hi:[0,1]
	v_pk_mul_f32 v[156:157], v[142:143], v[62:63] op_sel_hi:[0,1]
	v_pk_mul_f32 v[160:161], v[142:143], v[60:61] op_sel_hi:[0,1]
	v_pk_mul_f32 v[162:163], v[142:143], v[58:59] op_sel_hi:[0,1]
	v_lshl_add_u64 v[0:1], v[144:145], 0, v[0:1]
	v_cvt_pk_bf16_f32 v156, v156, v157
	v_cvt_pk_bf16_f32 v157, v158, v159
	v_cvt_pk_bf16_f32 v158, v162, v163
	v_cvt_pk_bf16_f32 v159, v160, v161
	global_store_dwordx4 v[0:1], v[156:159], off sc1
	v_pk_mul_f32 v[160:161], v[142:143], v[44:45] op_sel_hi:[0,1]
	v_pk_mul_f32 v[162:163], v[142:143], v[42:43] op_sel_hi:[0,1]
	v_pk_mul_f32 v[158:159], v[142:143], v[52:53] op_sel_hi:[0,1]
	v_pk_mul_f32 v[156:157], v[142:143], v[50:51] op_sel_hi:[0,1]
	v_cvt_pk_bf16_f32 v156, v156, v157
	v_cvt_pk_bf16_f32 v157, v158, v159
	v_cvt_pk_bf16_f32 v158, v162, v163
	v_cvt_pk_bf16_f32 v159, v160, v161
	global_store_dwordx4 v[0:1], v[156:159], off offset:256 sc1
	v_add_u32_e32 v0, 0x90, v146
	v_ashrrev_i32_e32 v1, 31, v0
	v_lshlrev_b64 v[0:1], 11, v[0:1]
	v_pk_mul_f32 v[158:159], v[142:143], v[56:57] op_sel_hi:[0,1]
	v_pk_mul_f32 v[156:157], v[142:143], v[54:55] op_sel_hi:[0,1]
	v_pk_mul_f32 v[160:161], v[142:143], v[48:49] op_sel_hi:[0,1]
	v_pk_mul_f32 v[162:163], v[142:143], v[46:47] op_sel_hi:[0,1]
	v_lshl_add_u64 v[0:1], v[144:145], 0, v[0:1]
	v_cvt_pk_bf16_f32 v156, v156, v157
	v_cvt_pk_bf16_f32 v157, v158, v159
	v_cvt_pk_bf16_f32 v158, v162, v163
	v_cvt_pk_bf16_f32 v159, v160, v161
	global_store_dwordx4 v[0:1], v[156:159], off sc1
	v_pk_mul_f32 v[160:161], v[142:143], v[28:29] op_sel_hi:[0,1]
	v_pk_mul_f32 v[162:163], v[142:143], v[26:27] op_sel_hi:[0,1]
	v_pk_mul_f32 v[158:159], v[142:143], v[36:37] op_sel_hi:[0,1]
	v_pk_mul_f32 v[156:157], v[142:143], v[34:35] op_sel_hi:[0,1]
	v_cvt_pk_bf16_f32 v156, v156, v157
	v_cvt_pk_bf16_f32 v157, v158, v159
	v_cvt_pk_bf16_f32 v158, v162, v163
	v_cvt_pk_bf16_f32 v159, v160, v161
	global_store_dwordx4 v[0:1], v[156:159], off offset:256 sc1
	v_add_u32_e32 v0, 0xa0, v146
	v_ashrrev_i32_e32 v1, 31, v0
	v_lshlrev_b64 v[0:1], 11, v[0:1]
	v_pk_mul_f32 v[158:159], v[142:143], v[40:41] op_sel_hi:[0,1]
	v_pk_mul_f32 v[156:157], v[142:143], v[38:39] op_sel_hi:[0,1]
	v_pk_mul_f32 v[160:161], v[142:143], v[32:33] op_sel_hi:[0,1]
	v_pk_mul_f32 v[162:163], v[142:143], v[30:31] op_sel_hi:[0,1]
	v_lshl_add_u64 v[0:1], v[144:145], 0, v[0:1]
	v_cvt_pk_bf16_f32 v156, v156, v157
	v_cvt_pk_bf16_f32 v157, v158, v159
	v_cvt_pk_bf16_f32 v158, v162, v163
	v_cvt_pk_bf16_f32 v159, v160, v161
	global_store_dwordx4 v[0:1], v[156:159], off sc1
	v_pk_mul_f32 v[160:161], v[142:143], v[12:13] op_sel_hi:[0,1]
	v_pk_mul_f32 v[162:163], v[142:143], v[10:11] op_sel_hi:[0,1]
	v_pk_mul_f32 v[158:159], v[142:143], v[20:21] op_sel_hi:[0,1]
	v_pk_mul_f32 v[156:157], v[142:143], v[18:19] op_sel_hi:[0,1]
	v_cvt_pk_bf16_f32 v156, v156, v157
	v_cvt_pk_bf16_f32 v157, v158, v159
	v_cvt_pk_bf16_f32 v158, v162, v163
	v_cvt_pk_bf16_f32 v159, v160, v161
	global_store_dwordx4 v[0:1], v[156:159], off offset:256 sc1
	v_add_u32_e32 v0, 0xb0, v146
	v_ashrrev_i32_e32 v1, 31, v0
	v_lshlrev_b64 v[0:1], 11, v[0:1]
	v_lshl_add_u64 v[0:1], v[144:145], 0, v[0:1]
	v_pk_mul_f32 v[146:147], v[142:143], v[24:25] op_sel_hi:[0,1]
	v_pk_mul_f32 v[144:145], v[142:143], v[22:23] op_sel_hi:[0,1]
	v_pk_mul_f32 v[156:157], v[142:143], v[16:17] op_sel_hi:[0,1]
	v_pk_mul_f32 v[158:159], v[142:143], v[14:15] op_sel_hi:[0,1]
	v_cvt_pk_bf16_f32 v144, v144, v145
	v_cvt_pk_bf16_f32 v145, v146, v147
	v_cvt_pk_bf16_f32 v146, v158, v159
	v_cvt_pk_bf16_f32 v147, v156, v157
	global_store_dwordx4 v[0:1], v[144:147], off sc1
	v_pk_mul_f32 v[156:157], v[142:143], v[4:5] op_sel_hi:[0,1]
	v_pk_mul_f32 v[158:159], v[142:143], v[2:3] op_sel_hi:[0,1]
	v_pk_mul_f32 v[146:147], v[142:143], v[8:9] op_sel_hi:[0,1]
	v_pk_mul_f32 v[144:145], v[142:143], v[6:7] op_sel_hi:[0,1]
	v_cvt_pk_bf16_f32 v144, v144, v145
	v_cvt_pk_bf16_f32 v145, v146, v147
	v_cvt_pk_bf16_f32 v146, v158, v159
	v_cvt_pk_bf16_f32 v147, v156, v157
	global_store_dwordx4 v[0:1], v[144:147], off offset:256 sc1
	s_cbranch_execnz .LBB0_1377
.LBB0_1380:
	s_lshl_b32 s0, s80, 8
	s_add_i32 s0, s0, s67
	s_lshr_b32 s1, s0, 9
	s_and_b32 s1, s1, 0x3ffffc
	v_or_b32_e32 v138, s0, v143
	s_or_b32 s1, s1, s64
	s_lshr_b32 s0, s0, 1
	s_lshl_b32 s1, s1, 10
	s_and_b32 s0, s0, 0x3e0
	s_or_b32 s0, s1, s0
	s_ashr_i32 s1, s0, 31
	s_lshl_b64 s[24:25], s[0:1], 10
	v_lshl_add_u64 v[0:1], v[140:141], 0, s[24:25]
	s_or_b32 s24, s0, 8
	s_mov_b32 s13, s9
	s_ashr_i32 s25, s24, 31
	v_cvt_pk_bf16_f32 v126, v126, v127
	v_cvt_pk_bf16_f32 v127, v128, v129
	v_cvt_pk_bf16_f32 v128, v122, v123
	v_lshl_add_u64 v[122:123], v[0:1], 0, s[8:9]
	v_cvt_pk_bf16_f32 v110, v110, v111
	v_cvt_pk_bf16_f32 v111, v112, v113
	v_cvt_pk_bf16_f32 v112, v106, v107
	v_cvt_pk_bf16_f32 v113, v108, v109
	v_lshl_add_u64 v[0:1], v[0:1], 0, s[12:13]
	s_lshl_b64 s[24:25], s[24:25], 10
	global_store_dwordx4 v[0:1], v[110:113], off sc1
	v_lshl_add_u64 v[0:1], v[140:141], 0, s[24:25]
	s_or_b32 s24, s0, 16
	s_ashr_i32 s25, s24, 31
	v_lshl_add_u64 v[110:111], v[0:1], 0, s[8:9]
	v_cvt_pk_bf16_f32 v94, v94, v95
	v_cvt_pk_bf16_f32 v95, v96, v97
	v_cvt_pk_bf16_f32 v96, v90, v91
	v_cvt_pk_bf16_f32 v97, v92, v93
	v_lshl_add_u64 v[0:1], v[0:1], 0, s[12:13]
	s_lshl_b64 s[24:25], s[24:25], 10
	s_or_b32 s0, s0, 24
	global_store_dwordx4 v[0:1], v[94:97], off sc1
	v_lshl_add_u64 v[0:1], v[140:141], 0, s[24:25]
	s_ashr_i32 s1, s0, 31
	v_lshl_add_u64 v[94:95], v[0:1], 0, s[8:9]
	v_cvt_pk_bf16_f32 v78, v78, v79
	v_cvt_pk_bf16_f32 v79, v80, v81
	v_cvt_pk_bf16_f32 v80, v74, v75
	v_cvt_pk_bf16_f32 v81, v76, v77
	v_lshl_add_u64 v[0:1], v[0:1], 0, s[12:13]
	s_lshl_b64 s[0:1], s[0:1], 10
	global_store_dwordx4 v[0:1], v[78:81], off sc1
	v_lshl_add_u64 v[0:1], v[140:141], 0, s[0:1]
	v_cvt_pk_bf16_f32 v70, v70, v71
	v_lshl_add_u64 v[78:79], v[0:1], 0, s[8:9]
	v_cvt_pk_bf16_f32 v71, v72, v73
	v_cvt_pk_bf16_f32 v72, v66, v67
	v_cvt_pk_bf16_f32 v73, v68, v69
	v_lshl_add_u64 v[0:1], v[0:1], 0, s[12:13]
	global_store_dwordx4 v[0:1], v[70:73], off sc1
	v_add_u32_e32 v0, 0x80, v138
	v_lshrrev_b32_e32 v1, 9, v0
	v_and_b32_e32 v1, 0x3ffffc, v1
	v_lshrrev_b32_e32 v0, 1, v0
	v_or_b32_e32 v1, s64, v1
	v_and_b32_e32 v0, 0x3e0, v0
	v_lshl_or_b32 v0, v1, 10, v0
	v_ashrrev_i32_e32 v1, 31, v0
	v_lshlrev_b64 v[0:1], 10, v[0:1]
	v_lshl_add_u64 v[0:1], v[140:141], 0, v[0:1]
	v_cvt_pk_bf16_f32 v129, v124, v125
	v_cvt_pk_bf16_f32 v106, v118, v119
	v_cvt_pk_bf16_f32 v107, v120, v121
	v_cvt_pk_bf16_f32 v108, v114, v115
	v_cvt_pk_bf16_f32 v109, v116, v117
	v_cvt_pk_bf16_f32 v90, v102, v103
	v_cvt_pk_bf16_f32 v91, v104, v105
	v_cvt_pk_bf16_f32 v92, v98, v99
	v_cvt_pk_bf16_f32 v93, v100, v101
	v_cvt_pk_bf16_f32 v74, v86, v87
	v_cvt_pk_bf16_f32 v75, v88, v89
	v_cvt_pk_bf16_f32 v76, v82, v83
	v_cvt_pk_bf16_f32 v77, v84, v85
	v_cvt_pk_bf16_f32 v62, v62, v63
	v_cvt_pk_bf16_f32 v63, v64, v65
	v_cvt_pk_bf16_f32 v64, v58, v59
	v_lshl_add_u64 v[58:59], v[0:1], 0, s[8:9]
	v_cvt_pk_bf16_f32 v50, v50, v51
	v_cvt_pk_bf16_f32 v51, v52, v53
	v_cvt_pk_bf16_f32 v52, v42, v43
	v_cvt_pk_bf16_f32 v53, v44, v45
	v_lshl_add_u64 v[0:1], v[0:1], 0, s[12:13]
	global_store_dwordx4 v[122:123], v[126:129], off sc1
	global_store_dwordx4 v[110:111], v[106:109], off sc1
	global_store_dwordx4 v[94:95], v[90:93], off sc1
	global_store_dwordx4 v[78:79], v[74:77], off sc1
	global_store_dwordx4 v[0:1], v[50:53], off sc1
	v_add_u32_e32 v0, 0x90, v138
	v_lshrrev_b32_e32 v1, 9, v0
	v_and_b32_e32 v1, 0x3ffffc, v1
	v_or_b32_e32 v1, s64, v1
	v_lshrrev_b32_e32 v0, 1, v0
	v_lshlrev_b32_e32 v1, 10, v1
	v_and_b32_e32 v0, 0x3e0, v0
	v_or3_b32 v0, v1, v0, 8
	v_ashrrev_i32_e32 v1, 31, v0
	v_lshlrev_b64 v[0:1], 10, v[0:1]
	v_lshl_add_u64 v[0:1], v[140:141], 0, v[0:1]
	v_cvt_pk_bf16_f32 v65, v60, v61
	v_cvt_pk_bf16_f32 v44, v46, v47
	v_lshl_add_u64 v[46:47], v[0:1], 0, s[8:9]
	v_cvt_pk_bf16_f32 v34, v34, v35
	v_cvt_pk_bf16_f32 v35, v36, v37
	v_cvt_pk_bf16_f32 v36, v26, v27
	v_cvt_pk_bf16_f32 v37, v28, v29
	v_lshl_add_u64 v[0:1], v[0:1], 0, s[12:13]
	global_store_dwordx4 v[58:59], v[62:65], off sc1
	global_store_dwordx4 v[0:1], v[34:37], off sc1
	v_add_u32_e32 v0, 0xa0, v138
	v_lshrrev_b32_e32 v1, 9, v0
	v_and_b32_e32 v1, 0x3ffffc, v1
	v_or_b32_e32 v1, s64, v1
	v_lshrrev_b32_e32 v0, 1, v0
	v_lshlrev_b32_e32 v1, 10, v1
	v_and_b32_e32 v0, 0x3e0, v0
	v_or3_b32 v0, v1, v0, 16
	v_ashrrev_i32_e32 v1, 31, v0
	v_lshlrev_b64 v[0:1], 10, v[0:1]
	v_lshl_add_u64 v[0:1], v[140:141], 0, v[0:1]
	v_cvt_pk_bf16_f32 v42, v54, v55
	v_cvt_pk_bf16_f32 v43, v56, v57
	v_cvt_pk_bf16_f32 v45, v48, v49
	v_cvt_pk_bf16_f32 v28, v30, v31
	v_lshl_add_u64 v[30:31], v[0:1], 0, s[8:9]
	v_cvt_pk_bf16_f32 v18, v18, v19
	v_cvt_pk_bf16_f32 v19, v20, v21
	v_cvt_pk_bf16_f32 v20, v10, v11
	v_cvt_pk_bf16_f32 v21, v12, v13
	v_lshl_add_u64 v[0:1], v[0:1], 0, s[12:13]
	global_store_dwordx4 v[46:47], v[42:45], off sc1
	global_store_dwordx4 v[0:1], v[18:21], off sc1
	v_add_u32_e32 v0, 0xb0, v138
	v_lshrrev_b32_e32 v1, 9, v0
	v_and_b32_e32 v1, 0x3ffffc, v1
	v_or_b32_e32 v1, s64, v1
	v_lshrrev_b32_e32 v0, 1, v0
	v_lshlrev_b32_e32 v1, 10, v1
	v_and_b32_e32 v0, 0x3e0, v0
	v_or3_b32 v0, v1, v0, 24
	v_ashrrev_i32_e32 v1, 31, v0
	v_lshlrev_b64 v[0:1], 10, v[0:1]
	v_lshl_add_u64 v[0:1], v[140:141], 0, v[0:1]
	v_cvt_pk_bf16_f32 v26, v38, v39
	v_cvt_pk_bf16_f32 v27, v40, v41
	v_cvt_pk_bf16_f32 v29, v32, v33
	v_cvt_pk_bf16_f32 v10, v22, v23
	v_cvt_pk_bf16_f32 v11, v24, v25
	v_cvt_pk_bf16_f32 v12, v14, v15
	v_cvt_pk_bf16_f32 v13, v16, v17
	v_lshl_add_u64 v[14:15], v[0:1], 0, s[8:9]
	v_cvt_pk_bf16_f32 v6, v6, v7
	v_cvt_pk_bf16_f32 v7, v8, v9
	v_cvt_pk_bf16_f32 v8, v2, v3
	v_cvt_pk_bf16_f32 v9, v4, v5
	v_lshl_add_u64 v[0:1], v[0:1], 0, s[12:13]
	global_store_dwordx4 v[30:31], v[26:29], off sc1
	global_store_dwordx4 v[14:15], v[10:13], off sc1
	global_store_dwordx4 v[0:1], v[6:9], off sc1
	s_andn2_b64 vcc, exec, s[20:21]
	s_mov_b64 s[0:1], -1
	s_cbranch_vccnz .LBB0_1369
